# all flat_load/flat_store (global pointers) converted to global_load/global_store
# speedup vs baseline: 1.0078x; 1.0034x over previous
; DI void phase0(const Params& p, char* smem) {
;     ...
;     int item = blockIdx.x;
;     if (item < NWP) { WDECODE(item, src, N, k0, n0, Kd, up, kind, dst); WLOAD(cur, src, N, k0, n0); }
;     for (; item < NWP; item += gridDim.x) {
;       const int nitem = item + gridDim.x;
;       if (nitem < NWP) { WDECODE(nitem, nsrc, nN, nk0, nn0, nKd, nup, nkind, ndst); WLOAD(nxt, nsrc, nN, nk0, nn0); }
.LBB0_18:
	s_or_b64 exec, exec, s[4:5]
	v_lshlrev_b32_e32 v4, 2, v66
	v_mov_b32_e32 v45, 0
	v_and_b32_e32 v20, 60, v4
	v_bfe_u32 v56, v66, 4, 4
	v_lshl_add_u64 v[2:3], v[44:45], 2, v[2:3]
	v_lshlrev_b32_e32 v22, 2, v20
	v_mov_b32_e32 v23, v45
	v_or_b32_e32 v19, v46, v56
	v_lshl_add_u64 v[12:13], v[2:3], 0, v[22:23]
	v_or_b32_e32 v2, 48, v19
	v_ashrrev_i32_e32 v5, 31, v46
	v_mul_lo_u32 v4, v11, v2
	v_mad_u64_u32 v[2:3], s[4:5], v10, v2, 0
	v_mul_lo_u32 v21, v10, v5
	v_add3_u32 v3, v3, v21, v4
	v_lshl_add_u64 v[14:15], v[2:3], 2, v[12:13]
	v_or_b32_e32 v2, 32, v19
	v_mul_lo_u32 v4, v11, v2
	v_mad_u64_u32 v[2:3], s[4:5], v10, v2, 0
	v_add3_u32 v3, v3, v21, v4
	v_lshl_add_u64 v[16:17], v[2:3], 2, v[12:13]
	global_load_dwordx4 v[2:5], v[14:15], off
	global_load_dwordx4 v[6:9], v[16:17], off
	v_or_b32_e32 v14, 16, v19
	v_mul_lo_u32 v16, v11, v14
	v_mad_u64_u32 v[14:15], s[4:5], v10, v14, 0
	v_add3_u32 v15, v15, v21, v16
	v_lshl_add_u64 v[24:25], v[14:15], 2, v[12:13]
	v_mul_lo_u32 v14, v11, v19
	v_mad_u64_u32 v[10:11], s[4:5], v10, v19, 0
	v_add3_u32 v11, v11, v21, v14
	v_lshl_add_u64 v[26:27], v[10:11], 2, v[12:13]
	global_load_dwordx4 v[10:13], v[24:25], off
	global_load_dwordx4 v[14:17], v[26:27], off
	s_movk_i32 s4, 0x4100
	v_mad_i32_i24 v19, v18, s4, 16
	v_add_u32_e32 v21, v19, v22
	v_lshlrev_b32_e32 v22, 4, v66
	v_and_b32_e32 v22, 48, v22
	v_mul_u32_u24_e32 v25, 0x41, v22
	v_and_b32_e32 v23, 0xfc, v66
	v_mul_u32_u24_e32 v24, 0x104, v56
	v_lshlrev_b32_e32 v25, 2, v25
	s_add_i32 s4, s54, s55
	v_bfe_u32 v57, v66, 2, 6
	v_add3_u32 v58, v19, v23, v25
	v_add3_u32 v59, v19, v25, v23
	v_lshl_add_u32 v60, s4, 1, v18
	s_lshl_b32 s12, s55, 1
	v_mov_b64_e32 v[54:55], 0
	s_mov_b32 s13, 0xb60b60b7
	s_movk_i32 s14, 0x1ff
	s_movk_i32 s15, 0x2ff
	s_movk_i32 s16, 0x87f
	s_mov_b32 s17, 0xb00000
	s_movk_i32 s18, 0x5bf
	s_mov_b32 s19, 0xba2e8ba3
	v_lshlrev_b32_e32 v50, 2, v20
	v_add_u32_e32 v61, v21, v24
	s_movk_i32 s20, 0x7f
	v_lshlrev_b32_e32 v52, 1, v22
	v_mov_b32_e32 v62, 0x7fffde00
	v_mov_b32_e32 v63, 0xfffffd00
	v_mov_b32_e32 v64, 0xfffffa40
	v_mov_b32_e32 v65, 0x7ffff800
	v_mov_b32_e32 v67, v44
	v_mov_b32_e32 v68, 0
	v_mov_b32_e32 v44, v45
	v_mov_b32_e32 v70, v45
	v_mov_b32_e32 v69, v45
	v_mov_b32_e32 v71, v45
	s_mov_b32 s21, s54
	s_branch .LBB0_21
.LBB0_19:
	s_or_b64 exec, exec, s[6:7]
	v_lshl_add_u64 v[18:19], v[44:45], 2, v[18:19]
	v_mov_b32_e32 v51, v45
	v_or_b32_e32 v32, v68, v56
	v_lshl_add_u64 v[28:29], v[18:19], 0, v[50:51]
	v_ashrrev_i32_e32 v18, 31, v68
	v_mul_lo_u32 v20, v27, v32
	v_mul_lo_u32 v33, v26, v18
	v_mad_u64_u32 v[18:19], s[6:7], v26, v32, 0
	v_or_b32_e32 v30, 32, v32
	v_add3_u32 v19, v19, v33, v20
	v_or_b32_e32 v20, 16, v32
	v_mul_lo_u32 v51, v27, v30
	v_mad_u64_u32 v[30:31], s[6:7], v26, v30, 0
	v_or_b32_e32 v32, 48, v32
	v_mul_lo_u32 v22, v27, v20
	v_mad_u64_u32 v[20:21], s[6:7], v26, v20, 0
	v_add3_u32 v31, v31, v33, v51
	v_mul_lo_u32 v51, v27, v32
	v_mad_u64_u32 v[26:27], s[6:7], v26, v32, 0
	v_add3_u32 v21, v21, v33, v22
	v_add3_u32 v27, v27, v33, v51
	v_lshl_add_u64 v[18:19], v[18:19], 2, v[28:29]
	v_lshl_add_u64 v[22:23], v[20:21], 2, v[28:29]
	v_lshl_add_u64 v[30:31], v[30:31], 2, v[28:29]
	v_lshl_add_u64 v[32:33], v[26:27], 2, v[28:29]
	global_load_dwordx4 v[18:21], v[18:19], off
	s_nop 0
	global_load_dwordx4 v[22:25], v[22:23], off
	s_nop 0
	global_load_dwordx4 v[26:29], v[30:31], off
	s_nop 0
	global_load_dwordx4 v[30:33], v[32:33], off

; DI void norm_row(const Params& p, int layer, int which, int t, int lane) {
;   const float* g = (which ? p.norm_ffn : p.norm_attn) + layer * DM;
;   const float* xr = which ? (const float*)xrow_dst(p, t) : xrow_src(p, layer, t);
;   const float* md = p.mod + ((size_t)layer * 5 + mb_of(t)) * 6144 + (which ? 3 * 1024 : 0);
;   float4 v[4];
;   float ss = 0.f;
; #pragma unroll
;   for (int j = 0; j < 4; ++j) {
;     v[j] = *(const float4*)(xr + lane * 4 + 256 * j);
;     ss += v[j].x * v[j].x + v[j].y * v[j].y + v[j].z * v[j].z + v[j].w * v[j].w;
;   }
; #pragma unroll
;   for (int o = 32; o >= 1; o >>= 1) ss += __shfl_xor(ss, o);
;   float r = rsqrtf(ss * (1.f / 1024.f) + EPSV);
; #pragma unroll
;   for (int j = 0; j < 4; ++j) {
;     int col = lane * 4 + 256 * j;
;     float4 gg = *(const float4*)(g + col);
;     float4 sh = *(const float4*)(md + col);
;     float4 sc = *(const float4*)(md + 1024 + col);
;     float o0 = v[j].x * r * gg.x * (1.f + sc.x) + sh.x;
;     float o1 = v[j].y * r * gg.y * (1.f + sc.y) + sh.y;
;     float o2 = v[j].z * r * gg.z * (1.f + sc.z) + sh.z;
;     float o3 = v[j].w * r * gg.w * (1.f + sc.w) + sh.w;
;     *(uint2*)(p.H + (size_t)t * LDK + col) = make_uint2(pack_bf16(o0, o1), pack_bf16(o2, o3));
;   }
; }
.LBB0_87:
	v_cmp_lt_i32_e32 vcc, v24, v23
	v_add_u32_e32 v36, 0x4000, v21
	v_mov_b64_e32 v[32:33], v[8:9]
	v_cndmask_b32_e32 v31, v22, v24, vcc
	v_cmp_lt_i32_e32 vcc, v25, v23
	v_mov_b64_e32 v[34:35], v[12:13]
	v_mov_b64_e32 v[38:39], v[6:7]
	v_cndmask_b32_e32 v42, v22, v25, vcc
	v_cmp_lt_i32_e32 vcc, v26, v23
	v_mov_b64_e32 v[40:41], v[10:11]
	v_ashrrev_i32_e32 v37, 31, v36
	v_cndmask_b32_e32 v43, v22, v26, vcc
	v_cmp_lt_i32_e32 vcc, v27, v23
	v_min_i32_e32 v47, 0x4000, v36
	v_lshlrev_b32_e32 v84, 2, v42
	v_cndmask_b32_e32 v44, v22, v27, vcc
	v_cmp_lt_i32_e32 vcc, v28, v23
	v_lshlrev_b32_e32 v85, 2, v43
	v_lshlrev_b32_e32 v86, 2, v44
	v_cndmask_b32_e32 v45, v22, v28, vcc
	v_cmp_lt_i32_e32 vcc, v29, v23
	v_ashrrev_i32_e32 v44, 12, v47
	v_lshlrev_b32_e32 v87, 2, v45
	v_cndmask_b32_e32 v46, v22, v29, vcc
	v_cmp_gt_i32_e32 vcc, s6, v36
	v_lshlrev_b32_e32 v88, 2, v46
	global_load_dwordx4 v[32:35], v[2:3], off
	v_cndmask_b32_e32 v43, 0, v37, vcc
	v_cndmask_b32_e32 v42, v21, v36, vcc
	v_cndmask_b32_e32 v39, v41, v39, vcc
	v_cndmask_b32_e32 v38, v40, v38, vcc
	v_lshlrev_b64 v[36:37], 11, v[36:37]
	v_lshlrev_b64 v[40:41], 12, v[42:43]
	v_mul_hi_i32_i24_e32 v43, 0x6000, v44
	v_mul_i32_i24_e32 v42, 0x6000, v44
	v_lshl_add_u64 v[60:61], v[4:5], 0, v[36:37]
	v_lshl_add_u64 v[36:37], v[38:39], 0, v[40:41]
	v_lshl_add_u64 v[38:39], s[62:63], 0, v[42:43]
	v_lshl_add_u64 v[48:49], v[36:37], 0, v[0:1]
	v_lshl_add_u64 v[62:63], v[38:39], 0, s[4:5]
	v_lshl_add_u64 v[64:65], v[38:39], 0, v[0:1]
	global_load_dwordx4 v[36:39], v[48:49], off
	global_load_dwordx4 v[40:43], v[48:49], off offset:1024
	global_load_dwordx4 v[44:47], v[48:49], off offset:2048
	s_nop 0
	global_load_dwordx4 v[48:51], v[48:49], off offset:3072
	v_lshl_add_u64 v[56:57], v[62:63], 0, v[0:1]
	global_load_dwordx4 v[52:55], v[64:65], off
	s_nop 0
	global_load_dwordx4 v[56:59], v[56:57], off
	v_lshlrev_b32_e32 v31, 2, v31
	v_lshl_add_u64 v[66:67], v[62:63], 0, v[14:15]
	v_add_u32_e32 v21, s7, v21
	s_waitcnt vmcnt(0) lgkmcnt(0)
	v_mov_b32_e32 v74, v37
	v_mov_b32_e32 v75, v41
	v_mov_b32_e32 v72, v36
	v_mov_b32_e32 v73, v40
	v_mov_b32_e32 v82, v45
	v_mov_b32_e32 v83, v49
	v_pk_mul_f32 v[74:75], v[74:75], v[74:75]
	v_mov_b32_e32 v68, v38
	v_mov_b32_e32 v69, v42
	v_mov_b32_e32 v80, v44
	v_mov_b32_e32 v81, v48
	v_pk_mul_f32 v[82:83], v[82:83], v[82:83]
	v_pk_fma_f32 v[72:73], v[72:73], v[72:73], v[74:75]
	v_mov_b32_e32 v70, v39
	v_mov_b32_e32 v71, v43
	v_mov_b32_e32 v76, v46
	v_mov_b32_e32 v77, v50
	v_pk_fma_f32 v[74:75], v[80:81], v[80:81], v[82:83]
	v_pk_fma_f32 v[68:69], v[68:69], v[68:69], v[72:73]
	v_mov_b32_e32 v78, v47
	v_mov_b32_e32 v79, v51
	v_pk_fma_f32 v[72:73], v[76:77], v[76:77], v[74:75]
	v_pk_fma_f32 v[68:69], v[70:71], v[70:71], v[68:69]
	v_pk_fma_f32 v[70:71], v[78:79], v[78:79], v[72:73]
	v_add_f32_e32 v68, v68, v69
	v_add_f32_e32 v68, v68, v70
	v_add_f32_e32 v68, v68, v71
	ds_bpermute_b32 v31, v31, v68
	v_pk_add_f32 v[56:57], v[56:57], 1.0 op_sel_hi:[1,0]
	v_pk_add_f32 v[58:59], v[58:59], 1.0 op_sel_hi:[1,0]
	s_waitcnt lgkmcnt(0)
	v_add_f32_e32 v31, v68, v31
	ds_bpermute_b32 v68, v84, v31
	s_waitcnt lgkmcnt(0)
	v_add_f32_e32 v31, v31, v68
	ds_bpermute_b32 v68, v85, v31
	s_waitcnt lgkmcnt(0)
	v_add_f32_e32 v31, v31, v68
	ds_bpermute_b32 v68, v86, v31
	s_waitcnt lgkmcnt(0)
	v_add_f32_e32 v31, v31, v68
	ds_bpermute_b32 v68, v87, v31
	s_waitcnt lgkmcnt(0)
	v_add_f32_e32 v31, v31, v68
	ds_bpermute_b32 v68, v88, v31
	s_waitcnt lgkmcnt(0)
	v_add_f32_e32 v31, v31, v68
	v_fmamk_f32 v31, v31, 0x3a800000, v30
	v_mul_f32_e32 v68, 0x4b800000, v31
	v_cmp_gt_f32_e32 vcc, s8, v31
	s_nop 1
	v_cndmask_b32_e32 v31, v31, v68, vcc
	v_rsq_f32_e32 v31, v31
	s_nop 0
	v_mul_f32_e32 v68, 0x45800000, v31
	v_cndmask_b32_e32 v68, v31, v68, vcc
	v_pk_mul_f32 v[36:37], v[36:37], v[68:69] op_sel_hi:[1,0]
	v_pk_mul_f32 v[38:39], v[38:39], v[68:69] op_sel_hi:[1,0]
	v_pk_mul_f32 v[32:33], v[32:33], v[36:37]
	v_pk_mul_f32 v[34:35], v[34:35], v[38:39]
	v_pk_fma_f32 v[32:33], v[56:57], v[32:33], v[52:53]
	v_pk_fma_f32 v[34:35], v[34:35], v[58:59], v[54:55]
	v_cvt_pk_bf16_f32 v32, v32, v33
	v_cvt_pk_bf16_f32 v33, v34, v35
	global_store_dwordx2 v[60:61], v[32:33], off
	global_load_dwordx4 v[32:35], v[2:3], off offset:1024
	s_nop 0
	global_load_dwordx4 v[36:39], v[66:67], off
	global_load_dwordx4 v[52:55], v[64:65], off offset:1024
	v_pk_mul_f32 v[40:41], v[40:41], v[68:69] op_sel_hi:[1,0]
	v_pk_mul_f32 v[42:43], v[42:43], v[68:69] op_sel_hi:[1,0]
	v_lshl_add_u64 v[56:57], v[62:63], 0, v[16:17]
	v_pk_mul_f32 v[44:45], v[44:45], v[68:69] op_sel_hi:[1,0]
	v_pk_mul_f32 v[46:47], v[46:47], v[68:69] op_sel_hi:[1,0]
	v_add_u32_e32 v31, 0x4000, v21
	v_cmp_lt_i32_e32 vcc, s9, v31
	s_or_b64 s[2:3], vcc, s[2:3]
	s_waitcnt vmcnt(2)
	v_pk_mul_f32 v[32:33], v[40:41], v[32:33]
	s_waitcnt vmcnt(1)
	v_pk_add_f32 v[36:37], v[36:37], 1.0 op_sel_hi:[1,0]
	v_pk_mul_f32 v[34:35], v[42:43], v[34:35]
	v_pk_add_f32 v[38:39], v[38:39], 1.0 op_sel_hi:[1,0]
	s_waitcnt vmcnt(0)
	v_pk_fma_f32 v[32:33], v[32:33], v[36:37], v[52:53]
	v_pk_fma_f32 v[34:35], v[34:35], v[38:39], v[54:55]
	v_cvt_pk_bf16_f32 v32, v32, v33
	v_cvt_pk_bf16_f32 v33, v34, v35
	global_store_dwordx2 v[60:61], v[32:33], off offset:512
	global_load_dwordx4 v[32:35], v[2:3], off offset:2048
	s_nop 0
	global_load_dwordx4 v[36:39], v[56:57], off
	global_load_dwordx4 v[40:43], v[64:65], off offset:2048
	v_lshl_add_u64 v[52:53], v[62:63], 0, v[18:19]
	s_waitcnt vmcnt(2)
	v_pk_mul_f32 v[32:33], v[44:45], v[32:33]
	s_waitcnt vmcnt(1)
	v_pk_add_f32 v[36:37], v[36:37], 1.0 op_sel_hi:[1,0]
	v_pk_mul_f32 v[34:35], v[46:47], v[34:35]
	v_pk_add_f32 v[38:39], v[38:39], 1.0 op_sel_hi:[1,0]
	s_waitcnt vmcnt(0)
	v_pk_fma_f32 v[32:33], v[32:33], v[36:37], v[40:41]
	v_pk_fma_f32 v[34:35], v[34:35], v[38:39], v[42:43]
	v_cvt_pk_bf16_f32 v32, v32, v33
	v_cvt_pk_bf16_f32 v33, v34, v35
	global_store_dwordx2 v[60:61], v[32:33], off offset:1024
	global_load_dwordx4 v[32:35], v[2:3], off offset:3072
	s_nop 0
	global_load_dwordx4 v[36:39], v[52:53], off
	global_load_dwordx4 v[40:43], v[64:65], off offset:3072
	v_pk_mul_f32 v[44:45], v[48:49], v[68:69] op_sel_hi:[1,0]
	v_pk_mul_f32 v[46:47], v[50:51], v[68:69] op_sel_hi:[1,0]
	s_waitcnt vmcnt(2)
	v_pk_mul_f32 v[32:33], v[44:45], v[32:33]
	s_waitcnt vmcnt(1)
	v_pk_add_f32 v[36:37], v[36:37], 1.0 op_sel_hi:[1,0]
	v_pk_mul_f32 v[34:35], v[46:47], v[34:35]
	v_pk_add_f32 v[38:39], v[38:39], 1.0 op_sel_hi:[1,0]
	s_waitcnt vmcnt(0)
	v_pk_fma_f32 v[32:33], v[32:33], v[36:37], v[40:41]
	v_pk_fma_f32 v[34:35], v[34:35], v[38:39], v[42:43]
	v_cvt_pk_bf16_f32 v32, v32, v33
	v_cvt_pk_bf16_f32 v33, v34, v35
	global_store_dwordx2 v[60:61], v[32:33], off offset:1536
	s_andn2_b64 exec, exec, s[2:3]
	s_cbranch_execnz .LBB0_87

;   DI void operator()(const f32x4 (&acc)[2][2][4][2], const Unit& u, int wr, int wc, int fr, int fq) const {
;     asm volatile("" ::: "memory");
;     const int row0 = u.pm * BM + wr * 64 + fr, col0 = u.pn * BM + wc * 32 + 4 * fq;
;     f32x4 gv[2][2];
; #pragma unroll
;     for (int bj = 0; bj < 2; ++bj)
; #pragma unroll
;       for (int n = 0; n < 2; ++n) gv[bj][n] = *(const f32x4*)(gate + col0 + bj * HALF + n * 16);
; #pragma unroll
;     for (int ai = 0; ai < 2; ++ai) {
;       f32x4 sv[4][2][2];
; #pragma unroll
;       for (int m = 0; m < 4; ++m) {
;         const size_t ro = (size_t)(row0 + ai * HALF + m * 16) * DM + col0;
; #pragma unroll
;         for (int bj = 0; bj < 2; ++bj)
; #pragma unroll
;           for (int n = 0; n < 2; ++n) sv[m][bj][n] = *(const f32x4*)(src + ro + bj * HALF + n * 16);
;       }
; #pragma unroll
;       for (int m = 0; m < 4; ++m) {
;         const size_t ro = (size_t)(row0 + ai * HALF + m * 16) * DM + col0;
; #pragma unroll
;         for (int bj = 0; bj < 2; ++bj)
; #pragma unroll
;           for (int n = 0; n < 2; ++n) *(f32x4*)(dst + ro + bj * HALF + n * 16) = sv[m][bj][n] + gv[bj][n] * acc[ai][bj][m][n];
;       }
;     }
;   }
.LBB0_138:
	s_ashr_i32 s2, s0, 4
	v_readlane_b32 s12, v254, 33
	s_lshl_b32 s1, s26, 8
	s_ashr_i32 s3, s2, 31
	s_mov_b32 s14, s12
	s_mul_i32 s12, s12, 5
	s_add_u32 s2, s12, s2
	s_mul_hi_u32 s12, s14, 5
	s_addc_u32 s3, s12, s3
	s_mulk_i32 s3, 0x6000
	s_mul_hi_u32 s12, s2, 0x6000
	v_lshl_or_b32 v0, v136, 2, s1
	s_add_i32 s12, s12, s3
	s_mulk_i32 s2, 0x6000
	v_or_b32_e32 v130, s27, v0
	s_add_u32 s2, s62, s2
	v_ashrrev_i32_e32 v131, 31, v130
	v_lshl_add_u32 v176, s0, 8, v148
	s_addc_u32 s3, s63, s12
	v_lshlrev_b64 v[146:147], 2, v[130:131]
	v_or_b32_e32 v168, 16, v176
	v_lshl_add_u64 v[130:131], s[2:3], 0, v[146:147]
	s_mov_b64 s[2:3], 0x5000
	s_movk_i32 s1, 0x5000
	v_ashrrev_i32_e32 v177, 31, v176
	v_ashrrev_i32_e32 v169, 31, v168
	v_lshl_add_u64 v[132:133], v[130:131], 0, s[2:3]
	v_add_co_u32_e32 v130, vcc, s1, v130
	v_lshl_add_u64 v[148:149], s[8:9], 0, v[146:147]
	v_lshlrev_b64 v[150:151], 12, v[176:177]
	v_lshlrev_b64 v[180:181], 12, v[168:169]
	v_addc_co_u32_e32 v131, vcc, 0, v131, vcc
	v_lshl_add_u64 v[164:165], v[148:149], 0, v[150:151]
	v_lshl_add_u64 v[182:183], v[148:149], 0, v[180:181]
	global_load_dwordx4 v[142:145], v[130:131], off
	global_load_dwordx4 v[138:141], v[132:133], off offset:64
	global_load_dwordx4 v[134:137], v[132:133], off offset:512
	s_nop 0
	global_load_dwordx4 v[130:133], v[132:133], off offset:576
	s_nop 0
	global_load_dwordx4 v[152:155], v[164:165], off
	global_load_dwordx4 v[156:159], v[164:165], off offset:64
	global_load_dwordx4 v[160:163], v[164:165], off offset:512
	s_nop 0
	global_load_dwordx4 v[164:167], v[164:165], off offset:576
	s_nop 0
	global_load_dwordx4 v[168:171], v[182:183], off
	global_load_dwordx4 v[172:175], v[182:183], off offset:64
	global_load_dwordx4 v[186:189], v[182:183], off offset:512
	global_load_dwordx4 v[190:193], v[182:183], off offset:576
	v_or_b32_e32 v182, 32, v176
	v_ashrrev_i32_e32 v183, 31, v182
	v_lshlrev_b64 v[182:183], 12, v[182:183]
	v_or_b32_e32 v176, 48, v176
	v_lshl_add_u64 v[184:185], v[148:149], 0, v[182:183]
	v_ashrrev_i32_e32 v177, 31, v176
	global_load_dwordx4 v[198:201], v[184:185], off
	global_load_dwordx4 v[202:205], v[184:185], off offset:64
	global_load_dwordx4 v[206:209], v[184:185], off offset:512
	global_load_dwordx4 v[214:217], v[184:185], off offset:576
	v_lshlrev_b64 v[176:177], 12, v[176:177]
	v_lshl_add_u64 v[184:185], v[148:149], 0, v[176:177]
	global_load_dwordx4 v[218:221], v[184:185], off
	global_load_dwordx4 v[222:225], v[184:185], off offset:64
	global_load_dwordx4 v[226:229], v[184:185], off offset:512
	global_load_dwordx4 v[230:233], v[184:185], off offset:576
	s_mov_b64 s[0:1], 0x80000
	s_cmpk_lt_u32 s25, 0x100
	v_readlane_b32 s13, v254, 34
	s_waitcnt vmcnt(0) lgkmcnt(0)
	v_pk_fma_f32 v[126:127], v[126:127], v[142:143], v[152:153]
	v_lshl_add_u64 v[152:153], s[8:9], 0, v[150:151]
	v_lshl_add_u64 v[152:153], v[152:153], 0, v[146:147]
	v_pk_fma_f32 v[116:117], v[116:117], v[132:133], v[166:167]
	v_pk_fma_f32 v[114:115], v[114:115], v[130:131], v[164:165]
	global_store_dwordx4 v[152:153], v[114:117], off offset:576
	v_pk_fma_f32 v[100:101], v[100:101], v[132:133], v[192:193]
	v_pk_fma_f32 v[98:99], v[98:99], v[130:131], v[190:191]
	v_lshl_add_u64 v[114:115], s[8:9], 0, v[180:181]
	v_lshl_add_u64 v[114:115], v[114:115], 0, v[146:147]
	global_store_dwordx4 v[114:115], v[98:101], off offset:576
	v_pk_fma_f32 v[84:85], v[84:85], v[132:133], v[216:217]
	v_pk_fma_f32 v[82:83], v[82:83], v[130:131], v[214:215]
	v_lshl_add_u64 v[98:99], s[8:9], 0, v[182:183]
	v_lshl_add_u64 v[98:99], v[98:99], 0, v[146:147]
	global_store_dwordx4 v[98:99], v[82:85], off offset:576
	v_pk_fma_f32 v[128:129], v[128:129], v[144:145], v[154:155]
	v_pk_fma_f32 v[124:125], v[124:125], v[140:141], v[158:159]
	v_lshl_add_u64 v[82:83], s[8:9], 0, v[176:177]
	v_pk_fma_f32 v[122:123], v[122:123], v[138:139], v[156:157]
	v_pk_fma_f32 v[120:121], v[120:121], v[136:137], v[162:163]
	v_pk_fma_f32 v[118:119], v[118:119], v[134:135], v[160:161]
	v_pk_fma_f32 v[112:113], v[112:113], v[144:145], v[170:171]
	v_pk_fma_f32 v[110:111], v[110:111], v[142:143], v[168:169]
	v_pk_fma_f32 v[108:109], v[108:109], v[140:141], v[174:175]
	v_pk_fma_f32 v[106:107], v[106:107], v[138:139], v[172:173]
	v_pk_fma_f32 v[104:105], v[104:105], v[136:137], v[188:189]
	v_pk_fma_f32 v[102:103], v[102:103], v[134:135], v[186:187]
	v_pk_fma_f32 v[96:97], v[96:97], v[144:145], v[200:201]
	v_pk_fma_f32 v[94:95], v[94:95], v[142:143], v[198:199]
	v_pk_fma_f32 v[92:93], v[92:93], v[140:141], v[204:205]
	v_pk_fma_f32 v[90:91], v[90:91], v[138:139], v[202:203]
	v_pk_fma_f32 v[88:89], v[88:89], v[136:137], v[208:209]
	v_pk_fma_f32 v[86:87], v[86:87], v[134:135], v[206:207]
	v_pk_fma_f32 v[80:81], v[80:81], v[144:145], v[220:221]
	v_pk_fma_f32 v[78:79], v[78:79], v[142:143], v[218:219]
	v_lshl_add_u64 v[82:83], v[82:83], 0, v[146:147]
	v_pk_fma_f32 v[76:77], v[76:77], v[140:141], v[224:225]
	v_pk_fma_f32 v[74:75], v[74:75], v[138:139], v[222:223]
	v_pk_fma_f32 v[72:73], v[72:73], v[136:137], v[228:229]
	v_pk_fma_f32 v[70:71], v[70:71], v[134:135], v[226:227]
	v_pk_fma_f32 v[68:69], v[68:69], v[132:133], v[232:233]
	v_pk_fma_f32 v[66:67], v[66:67], v[130:131], v[230:231]
; #define PG8_WAIT_V(n) asm volatile("s_waitcnt vmcnt(" #n ")" ::: "memory")
; #define PG8_BAR __builtin_amdgcn_s_barrier()
; template <class Epi, class Sched>
; DI void gemm_phase(LAS unsigned char* lds, const Gemm g, const Sched& S, const Epi& E) {
;     ...
;   PG8_WAIT_V(0);
;   if (wr == 0) PG8_BAR;
;   PG8_BAR;
;   DI void operator()(const f32x4 (&acc)[2][2][4][2], const Unit& u, int wr, int wc, int fr, int fq) const {
;     asm volatile("" ::: "memory");
;     const int row0 = u.pm * BM + wr * 64 + fr, col0 = u.pn * BM + wc * 32 + 4 * fq;
;     f32x4 gv[2][2];
; #pragma unroll
;     for (int bj = 0; bj < 2; ++bj)
; #pragma unroll
;       for (int n = 0; n < 2; ++n) gv[bj][n] = *(const f32x4*)(gate + col0 + bj * HALF + n * 16);
; #pragma unroll
;     for (int ai = 0; ai < 2; ++ai) {
;       f32x4 sv[4][2][2];
; #pragma unroll
;       for (int m = 0; m < 4; ++m) {
;         const size_t ro = (size_t)(row0 + ai * HALF + m * 16) * DM + col0;
; #pragma unroll
;         for (int bj = 0; bj < 2; ++bj)
; #pragma unroll
;           for (int n = 0; n < 2; ++n) sv[m][bj][n] = *(const f32x4*)(src + ro + bj * HALF + n * 16);
;       }
; #pragma unroll
;       for (int m = 0; m < 4; ++m) {
;         const size_t ro = (size_t)(row0 + ai * HALF + m * 16) * DM + col0;
; #pragma unroll
;         for (int bj = 0; bj < 2; ++bj)
; #pragma unroll
;           for (int n = 0; n < 2; ++n) *(f32x4*)(dst + ro + bj * HALF + n * 16) = sv[m][bj][n] + gv[bj][n] * acc[ai][bj][m][n];
;       }
;     }
;   }
	v_lshl_add_u64 v[156:157], v[150:151], 0, s[0:1]
	global_store_dwordx4 v[152:153], v[126:129], off
	global_store_dwordx4 v[152:153], v[122:125], off offset:64
	global_store_dwordx4 v[152:153], v[118:121], off offset:512
	global_store_dwordx4 v[114:115], v[110:113], off
	global_store_dwordx4 v[114:115], v[106:109], off offset:64
	global_store_dwordx4 v[114:115], v[102:105], off offset:512
	global_store_dwordx4 v[98:99], v[94:97], off
	global_store_dwordx4 v[98:99], v[90:93], off offset:64
	global_store_dwordx4 v[98:99], v[86:89], off offset:512
	global_store_dwordx4 v[82:83], v[78:81], off
	global_store_dwordx4 v[82:83], v[74:77], off offset:64
	global_store_dwordx4 v[82:83], v[70:73], off offset:512
	global_store_dwordx4 v[82:83], v[66:69], off offset:576
	s_mov_b64 s[0:1], 0x90000
	v_lshl_add_u64 v[154:155], v[150:151], 0, s[0:1]
	v_lshl_add_u64 v[66:67], v[148:149], 0, v[156:157]
	global_load_dwordx4 v[94:97], v[66:67], off
	global_load_dwordx4 v[90:93], v[66:67], off offset:64
	global_load_dwordx4 v[86:89], v[66:67], off offset:512
	global_load_dwordx4 v[78:81], v[66:67], off offset:576
	v_lshl_add_u64 v[66:67], v[148:149], 0, v[154:155]
	s_mov_b64 s[0:1], 0xa0000
	global_load_dwordx4 v[82:85], v[66:67], off
	global_load_dwordx4 v[74:77], v[66:67], off offset:64
	global_load_dwordx4 v[70:73], v[66:67], off offset:512
	s_nop 0
	global_load_dwordx4 v[66:69], v[66:67], off offset:576
	v_lshl_add_u64 v[152:153], v[150:151], 0, s[0:1]
	v_lshl_add_u64 v[98:99], v[148:149], 0, v[152:153]
	s_mov_b64 s[0:1], 0xb0000
	global_load_dwordx4 v[122:125], v[98:99], off
	global_load_dwordx4 v[126:129], v[98:99], off offset:64
	global_load_dwordx4 v[118:121], v[98:99], off offset:512
	global_load_dwordx4 v[114:117], v[98:99], off offset:576
	v_lshl_add_u64 v[150:151], v[150:151], 0, s[0:1]
	v_lshl_add_u64 v[98:99], v[148:149], 0, v[150:151]
	global_load_dwordx4 v[106:109], v[98:99], off
	global_load_dwordx4 v[110:113], v[98:99], off offset:64
	global_load_dwordx4 v[102:105], v[98:99], off offset:512
	s_nop 0
	global_load_dwordx4 v[98:101], v[98:99], off offset:576
	s_waitcnt vmcnt(0) lgkmcnt(0)
	v_pk_fma_f32 v[62:63], v[62:63], v[142:143], v[94:95]
	v_lshl_add_u64 v[94:95], s[8:9], 0, v[156:157]
	v_lshl_add_u64 v[94:95], v[94:95], 0, v[146:147]
	v_pk_fma_f32 v[52:53], v[52:53], v[132:133], v[80:81]
	v_pk_fma_f32 v[50:51], v[50:51], v[130:131], v[78:79]
	global_store_dwordx4 v[94:95], v[50:53], off offset:576
	v_pk_fma_f32 v[36:37], v[36:37], v[132:133], v[68:69]
	v_pk_fma_f32 v[34:35], v[34:35], v[130:131], v[66:67]
	v_lshl_add_u64 v[50:51], s[8:9], 0, v[154:155]
	v_lshl_add_u64 v[50:51], v[50:51], 0, v[146:147]
	global_store_dwordx4 v[50:51], v[34:37], off offset:576
	v_pk_fma_f32 v[20:21], v[20:21], v[132:133], v[116:117]
	v_pk_fma_f32 v[18:19], v[18:19], v[130:131], v[114:115]
	v_lshl_add_u64 v[34:35], s[8:9], 0, v[152:153]
	v_lshl_add_u64 v[34:35], v[34:35], 0, v[146:147]
	global_store_dwordx4 v[34:35], v[18:21], off offset:576
	v_pk_fma_f32 v[64:65], v[64:65], v[144:145], v[96:97]
	v_pk_fma_f32 v[60:61], v[60:61], v[140:141], v[92:93]
	v_lshl_add_u64 v[18:19], s[8:9], 0, v[150:151]
	v_pk_fma_f32 v[58:59], v[58:59], v[138:139], v[90:91]
	v_pk_fma_f32 v[56:57], v[56:57], v[136:137], v[88:89]
	v_pk_fma_f32 v[54:55], v[54:55], v[134:135], v[86:87]
	v_pk_fma_f32 v[48:49], v[48:49], v[144:145], v[84:85]
	v_pk_fma_f32 v[46:47], v[46:47], v[142:143], v[82:83]
	v_pk_fma_f32 v[44:45], v[44:45], v[140:141], v[76:77]
	v_pk_fma_f32 v[42:43], v[42:43], v[138:139], v[74:75]
	v_pk_fma_f32 v[40:41], v[40:41], v[136:137], v[72:73]
	v_pk_fma_f32 v[38:39], v[38:39], v[134:135], v[70:71]
	v_pk_fma_f32 v[32:33], v[32:33], v[144:145], v[124:125]
	v_pk_fma_f32 v[30:31], v[30:31], v[142:143], v[122:123]
	v_pk_fma_f32 v[28:29], v[28:29], v[140:141], v[128:129]
	v_pk_fma_f32 v[26:27], v[26:27], v[138:139], v[126:127]
	v_pk_fma_f32 v[24:25], v[24:25], v[136:137], v[120:121]
	v_pk_fma_f32 v[22:23], v[22:23], v[134:135], v[118:119]
	v_pk_fma_f32 v[16:17], v[16:17], v[144:145], v[108:109]
	v_pk_fma_f32 v[14:15], v[14:15], v[142:143], v[106:107]
	v_lshl_add_u64 v[18:19], v[18:19], 0, v[146:147]
	v_pk_fma_f32 v[12:13], v[12:13], v[140:141], v[112:113]
	v_pk_fma_f32 v[10:11], v[10:11], v[138:139], v[110:111]
	v_pk_fma_f32 v[8:9], v[8:9], v[136:137], v[104:105]
	v_pk_fma_f32 v[6:7], v[6:7], v[134:135], v[102:103]
	v_pk_fma_f32 v[4:5], v[4:5], v[132:133], v[100:101]
	v_pk_fma_f32 v[2:3], v[2:3], v[130:131], v[98:99]
	global_store_dwordx4 v[94:95], v[62:65], off
	global_store_dwordx4 v[94:95], v[58:61], off offset:64
	global_store_dwordx4 v[94:95], v[54:57], off offset:512
	global_store_dwordx4 v[50:51], v[46:49], off
	global_store_dwordx4 v[50:51], v[42:45], off offset:64
	global_store_dwordx4 v[50:51], v[38:41], off offset:512
	global_store_dwordx4 v[34:35], v[30:33], off
	global_store_dwordx4 v[34:35], v[26:29], off offset:64
	global_store_dwordx4 v[34:35], v[22:25], off offset:512
	global_store_dwordx4 v[18:19], v[14:17], off
	global_store_dwordx4 v[18:19], v[10:13], off offset:64
	global_store_dwordx4 v[18:19], v[6:9], off offset:512
	global_store_dwordx4 v[18:19], v[2:5], off offset:576
	s_waitcnt vmcnt(0)
	s_cbranch_scc0 .LBB0_126
	s_barrier
	s_branch .LBB0_126

; DI void norm_row(const Params& p, int layer, int which, int t, int lane) {
;   const float* g = (which ? p.norm_ffn : p.norm_attn) + layer * DM;
;   const float* xr = which ? (const float*)xrow_dst(p, t) : xrow_src(p, layer, t);
;   const float* md = p.mod + ((size_t)layer * 5 + mb_of(t)) * 6144 + (which ? 3 * 1024 : 0);
;   float4 v[4];
;   float ss = 0.f;
; #pragma unroll
;   for (int j = 0; j < 4; ++j) {
;     v[j] = *(const float4*)(xr + lane * 4 + 256 * j);
;     ss += v[j].x * v[j].x + v[j].y * v[j].y + v[j].z * v[j].z + v[j].w * v[j].w;
;   }
; #pragma unroll
;   for (int o = 32; o >= 1; o >>= 1) ss += __shfl_xor(ss, o);
;   float r = rsqrtf(ss * (1.f / 1024.f) + EPSV);
; #pragma unroll
;   for (int j = 0; j < 4; ++j) {
;     int col = lane * 4 + 256 * j;
;     float4 gg = *(const float4*)(g + col);
;     float4 sh = *(const float4*)(md + col);
;     float4 sc = *(const float4*)(md + 1024 + col);
;     float o0 = v[j].x * r * gg.x * (1.f + sc.x) + sh.x;
;     float o1 = v[j].y * r * gg.y * (1.f + sc.y) + sh.y;
;     float o2 = v[j].z * r * gg.z * (1.f + sc.z) + sh.z;
;     float o3 = v[j].w * r * gg.w * (1.f + sc.w) + sh.w;
;     *(uint2*)(p.H + (size_t)t * LDK + col) = make_uint2(pack_bf16(o0, o1), pack_bf16(o2, o3));
;   }
; }
.LBB0_143:
	v_add_u32_e32 v2, 0x4000, v50
	v_mov_b64_e32 v[4:5], s[36:37]
	v_mov_b64_e32 v[6:7], s[76:77]
	v_mov_b64_e32 v[8:9], s[40:41]
	v_mov_b64_e32 v[10:11], s[64:65]
	v_cmp_gt_i32_e32 vcc, s13, v2
	v_ashrrev_i32_e32 v3, 31, v2
	v_cndmask_b32_e64 v8, v10, v8, s[4:5]
	v_cndmask_b32_e64 v9, v11, v9, s[4:5]
	v_cndmask_b32_e64 v6, v6, v4, s[4:5]
	v_cndmask_b32_e64 v7, v7, v5, s[4:5]
	v_cndmask_b32_e32 v5, 0, v3, vcc
	v_cndmask_b32_e32 v4, v50, v2, vcc
	v_cndmask_b32_e32 v7, v9, v7, vcc
	v_cndmask_b32_e32 v6, v8, v6, vcc
	v_lshlrev_b64 v[4:5], 12, v[4:5]
	v_lshl_add_u64 v[4:5], v[6:7], 0, v[4:5]
	v_lshl_add_u64 v[14:15], v[4:5], 0, v[0:1]
	v_and_b32_e32 v4, 64, v211
	v_add_u32_e32 v4, 64, v4
	v_xor_b32_e32 v5, 32, v211
	v_cmp_lt_i32_e32 vcc, v5, v4
	v_min_i32_e32 v6, 0x4000, v2
	v_ashrrev_i32_e32 v6, 12, v6
	v_cndmask_b32_e32 v5, v211, v5, vcc
	v_lshlrev_b32_e32 v51, 2, v5
	v_xor_b32_e32 v5, 16, v211
	v_cmp_lt_i32_e32 vcc, v5, v4
	v_add_u32_e32 v6, s12, v6
	v_mul_hi_i32_i24_e32 v7, 0x6000, v6
	v_cndmask_b32_e32 v5, v211, v5, vcc
	v_lshlrev_b32_e32 v52, 2, v5
	v_xor_b32_e32 v5, 8, v211
	v_cmp_lt_i32_e32 vcc, v5, v4
	v_mul_i32_i24_e32 v6, 0x6000, v6
	v_lshl_add_u64 v[6:7], s[62:63], 0, v[6:7]
	v_cndmask_b32_e32 v5, v211, v5, vcc
	v_lshlrev_b32_e32 v53, 2, v5
	v_xor_b32_e32 v5, 4, v211
	v_cmp_lt_i32_e32 vcc, v5, v4
	v_lshl_add_u64 v[16:17], v[6:7], 0, s[18:19]
	v_lshl_add_u64 v[18:19], v[16:17], 0, v[0:1]
	v_cndmask_b32_e32 v5, v211, v5, vcc
	v_lshlrev_b32_e32 v64, 2, v5
	v_xor_b32_e32 v5, 2, v211
	v_cmp_lt_i32_e32 vcc, v5, v4
	v_lshlrev_b64 v[22:23], 11, v[2:3]
	v_lshl_add_u64 v[38:39], v[6:7], 0, v[0:1]
	v_cndmask_b32_e32 v5, v211, v5, vcc
	v_lshlrev_b32_e32 v65, 2, v5
	v_xor_b32_e32 v5, 1, v211
	v_cmp_lt_i32_e32 vcc, v5, v4
	v_lshl_add_u64 v[36:37], v[28:29], 0, v[22:23]
	v_mov_b32_e32 v31, v1
	v_cndmask_b32_e32 v4, v211, v5, vcc
	s_waitcnt vmcnt(0)
	v_lshlrev_b32_e32 v66, 2, v4
	global_load_dwordx4 v[10:13], v[14:15], off
	global_load_dwordx4 v[6:9], v[26:27], off
	global_load_dwordx4 v[2:5], v[38:39], off
	s_nop 0
	global_load_dwordx4 v[18:21], v[18:19], off
	v_mov_b32_e32 v33, v1
	v_mov_b32_e32 v35, v1
	v_lshl_add_u64 v[44:45], v[16:17], 0, v[30:31]
	v_add_u32_e32 v50, s14, v50
	s_waitcnt vmcnt(0) lgkmcnt(0)
	v_mov_b32_e32 v48, v11
	v_mov_b32_e32 v46, v10
	v_mov_b32_e32 v22, v12
	v_pk_add_f32 v[42:43], v[18:19], 1.0 op_sel_hi:[1,0]
	v_pk_add_f32 v[40:41], v[20:21], 1.0 op_sel_hi:[1,0]
	global_load_dwordx4 v[18:21], v[14:15], off offset:1024
	v_mov_b32_e32 v24, v13
	s_waitcnt vmcnt(0) lgkmcnt(0)
	v_mov_b32_e32 v49, v19
	v_mov_b32_e32 v47, v18
	v_pk_mul_f32 v[48:49], v[48:49], v[48:49]
	v_mov_b32_e32 v23, v20
	v_pk_fma_f32 v[46:47], v[46:47], v[46:47], v[48:49]
	v_mov_b32_e32 v25, v21
	v_pk_fma_f32 v[22:23], v[22:23], v[22:23], v[46:47]
	v_lshl_add_u64 v[46:47], v[16:17], 0, v[32:33]
	v_pk_fma_f32 v[54:55], v[24:25], v[24:25], v[22:23]
	global_load_dwordx4 v[22:25], v[14:15], off offset:2048
	v_lshl_add_u64 v[48:49], v[16:17], 0, v[34:35]
	global_load_dwordx4 v[14:17], v[14:15], off offset:3072
	v_add_f32_e32 v31, v54, v55
	s_waitcnt vmcnt(0) lgkmcnt(0)
	v_mov_b32_e32 v62, v23
	v_mov_b32_e32 v60, v22
	v_mov_b32_e32 v63, v15
	v_mov_b32_e32 v61, v14
	v_pk_mul_f32 v[62:63], v[62:63], v[62:63]
	v_mov_b32_e32 v56, v24
	v_mov_b32_e32 v57, v16
	v_pk_fma_f32 v[60:61], v[60:61], v[60:61], v[62:63]
	v_mov_b32_e32 v58, v25
	v_mov_b32_e32 v59, v17
	v_pk_fma_f32 v[56:57], v[56:57], v[56:57], v[60:61]
	s_nop 0
	v_pk_fma_f32 v[56:57], v[58:59], v[58:59], v[56:57]
	s_nop 0
	v_add_f32_e32 v31, v31, v56
	v_add_f32_e32 v31, v31, v57
	ds_bpermute_b32 v33, v51, v31
	s_waitcnt lgkmcnt(0)
; DI void norm_row(const Params& p, int layer, int which, int t, int lane) {
;     ...
;   for (int o = 32; o >= 1; o >>= 1) ss += __shfl_xor(ss, o);
;   float r = rsqrtf(ss * (1.f / 1024.f) + EPSV);
; #pragma unroll
;   for (int j = 0; j < 4; ++j) {
;     int col = lane * 4 + 256 * j;
;     float4 gg = *(const float4*)(g + col);
;     float4 sh = *(const float4*)(md + col);
;     float4 sc = *(const float4*)(md + 1024 + col);
;     float o0 = v[j].x * r * gg.x * (1.f + sc.x) + sh.x;
;     float o1 = v[j].y * r * gg.y * (1.f + sc.y) + sh.y;
;     float o2 = v[j].z * r * gg.z * (1.f + sc.z) + sh.z;
;     float o3 = v[j].w * r * gg.w * (1.f + sc.w) + sh.w;
;     *(uint2*)(p.H + (size_t)t * LDK + col) = make_uint2(pack_bf16(o0, o1), pack_bf16(o2, o3));
;   }
	v_add_f32_e32 v31, v31, v33
	ds_bpermute_b32 v33, v52, v31
	s_waitcnt lgkmcnt(0)
	v_add_f32_e32 v31, v31, v33
	ds_bpermute_b32 v33, v53, v31
	s_waitcnt lgkmcnt(0)
	v_add_f32_e32 v31, v31, v33
	ds_bpermute_b32 v33, v64, v31
	s_waitcnt lgkmcnt(0)
	v_add_f32_e32 v31, v31, v33
	ds_bpermute_b32 v33, v65, v31
	s_waitcnt lgkmcnt(0)
	v_add_f32_e32 v31, v31, v33
	ds_bpermute_b32 v33, v66, v31
	s_waitcnt lgkmcnt(0)
	v_add_f32_e32 v31, v31, v33
	v_fmamk_f32 v31, v31, 0x3a800000, v210
	v_cmp_gt_f32_e32 vcc, s15, v31
	v_mul_f32_e32 v33, 0x4b800000, v31
	s_nop 0
	v_cndmask_b32_e32 v31, v31, v33, vcc
	v_rsq_f32_e32 v31, v31
	s_nop 0
	v_mul_f32_e32 v33, 0x45800000, v31
	v_cndmask_b32_e32 v52, v31, v33, vcc
	v_pk_mul_f32 v[10:11], v[10:11], v[52:53] op_sel_hi:[1,0]
	v_pk_mul_f32 v[18:19], v[18:19], v[52:53] op_sel_hi:[1,0]
	v_pk_mul_f32 v[6:7], v[6:7], v[10:11]
	v_pk_mul_f32 v[14:15], v[14:15], v[52:53] op_sel_hi:[1,0]
	v_pk_fma_f32 v[2:3], v[42:43], v[6:7], v[2:3]
	v_pk_mul_f32 v[6:7], v[12:13], v[52:53] op_sel_hi:[1,0]
	v_cvt_pk_bf16_f32 v2, v2, v3
	v_pk_mul_f32 v[6:7], v[8:9], v[6:7]
	s_nop 0
	v_pk_fma_f32 v[4:5], v[6:7], v[40:41], v[4:5]
	s_nop 0
	v_cvt_pk_bf16_f32 v3, v4, v5
	global_store_dwordx2 v[36:37], v[2:3], off
	global_load_dwordx4 v[2:5], v[26:27], off offset:1024
	s_nop 0
	global_load_dwordx4 v[6:9], v[38:39], off offset:1024
	global_load_dwordx4 v[10:13], v[44:45], off
	s_waitcnt vmcnt(2)
	v_pk_mul_f32 v[2:3], v[18:19], v[2:3]
	v_pk_mul_f32 v[18:19], v[22:23], v[52:53] op_sel_hi:[1,0]
	s_waitcnt vmcnt(0)
	v_pk_add_f32 v[10:11], v[10:11], 1.0 op_sel_hi:[1,0]
	s_nop 0
	v_pk_fma_f32 v[2:3], v[2:3], v[10:11], v[6:7]
	v_pk_mul_f32 v[6:7], v[20:21], v[52:53] op_sel_hi:[1,0]
	v_cvt_pk_bf16_f32 v2, v2, v3
	v_pk_mul_f32 v[4:5], v[6:7], v[4:5]
	v_pk_add_f32 v[6:7], v[12:13], 1.0 op_sel_hi:[1,0]
	s_nop 0
	v_pk_fma_f32 v[4:5], v[4:5], v[6:7], v[8:9]
	s_nop 0
	v_cvt_pk_bf16_f32 v3, v4, v5
	global_store_dwordx2 v[36:37], v[2:3], off offset:512
	global_load_dwordx4 v[2:5], v[26:27], off offset:2048
	s_nop 0
	global_load_dwordx4 v[6:9], v[38:39], off offset:2048
	global_load_dwordx4 v[10:13], v[46:47], off
	s_waitcnt vmcnt(2)
	v_pk_mul_f32 v[2:3], v[18:19], v[2:3]
	s_waitcnt vmcnt(0)
	v_pk_add_f32 v[10:11], v[10:11], 1.0 op_sel_hi:[1,0]
	s_nop 0
	v_pk_fma_f32 v[2:3], v[2:3], v[10:11], v[6:7]
	v_pk_mul_f32 v[6:7], v[24:25], v[52:53] op_sel_hi:[1,0]
	v_cvt_pk_bf16_f32 v2, v2, v3
	v_pk_mul_f32 v[4:5], v[6:7], v[4:5]
	v_pk_add_f32 v[6:7], v[12:13], 1.0 op_sel_hi:[1,0]
	s_nop 0
	v_pk_fma_f32 v[4:5], v[4:5], v[6:7], v[8:9]
	s_nop 0
	v_cvt_pk_bf16_f32 v3, v4, v5
	global_store_dwordx2 v[36:37], v[2:3], off offset:1024
	global_load_dwordx4 v[2:5], v[26:27], off offset:3072
	s_nop 0
	global_load_dwordx4 v[6:9], v[38:39], off offset:3072
	global_load_dwordx4 v[10:13], v[48:49], off
	s_waitcnt vmcnt(2)
	v_pk_mul_f32 v[2:3], v[14:15], v[2:3]
	s_waitcnt vmcnt(0)
	v_pk_add_f32 v[10:11], v[10:11], 1.0 op_sel_hi:[1,0]
	s_nop 0
	v_pk_fma_f32 v[2:3], v[2:3], v[10:11], v[6:7]
	v_pk_mul_f32 v[6:7], v[16:17], v[52:53] op_sel_hi:[1,0]
	v_cvt_pk_bf16_f32 v2, v2, v3
	v_pk_mul_f32 v[4:5], v[6:7], v[4:5]
	v_pk_add_f32 v[6:7], v[12:13], 1.0 op_sel_hi:[1,0]
	s_nop 0
	v_pk_fma_f32 v[4:5], v[4:5], v[6:7], v[8:9]
	s_nop 0
	v_cvt_pk_bf16_f32 v3, v4, v5
	global_store_dwordx2 v[36:37], v[2:3], off offset:1536
	v_add_u32_e32 v2, 0x4000, v50
	v_cmp_lt_i32_e32 vcc, s16, v2
	s_or_b64 s[2:3], vcc, s[2:3]
	s_andn2_b64 exec, exec, s[2:3]
	s_cbranch_execnz .LBB0_143

;   DI void operator()(const f32x4 (&acc)[2][2][4][2], const Unit& u, int wr, int wc, int fr, int fq) const {
;     asm volatile("" ::: "memory");
;     const int row0 = u.pm * BM + wr * 64 + fr, col0 = u.pn * BM + wc * 32 + 4 * fq;
;     f32x4 gv[2][2];
; #pragma unroll
;     for (int bj = 0; bj < 2; ++bj)
; #pragma unroll
;       for (int n = 0; n < 2; ++n) gv[bj][n] = *(const f32x4*)(gate + col0 + bj * HALF + n * 16);
; #pragma unroll
;     for (int ai = 0; ai < 2; ++ai) {
;       f32x4 sv[4][2][2];
; #pragma unroll
;       for (int m = 0; m < 4; ++m) {
;         const size_t ro = (size_t)(row0 + ai * HALF + m * 16) * DM + col0;
; #pragma unroll
;         for (int bj = 0; bj < 2; ++bj)
; #pragma unroll
;           for (int n = 0; n < 2; ++n) sv[m][bj][n] = *(const f32x4*)(src + ro + bj * HALF + n * 16);
;       }
; #pragma unroll
;       for (int m = 0; m < 4; ++m) {
;         const size_t ro = (size_t)(row0 + ai * HALF + m * 16) * DM + col0;
; #pragma unroll
;         for (int bj = 0; bj < 2; ++bj)
; #pragma unroll
;           for (int n = 0; n < 2; ++n) *(f32x4*)(dst + ro + bj * HALF + n * 16) = sv[m][bj][n] + gv[bj][n] * acc[ai][bj][m][n];
;       }
;     }
;   }
.LBB0_154:
	v_readlane_b32 s2, v252, 41
	s_mul_i32 s21, s21, 0x1e000
	s_add_u32 s0, s62, s21
	v_lshl_or_b32 v0, v136, 2, s2
	v_or_b32_e32 v0, s22, v0
	s_addc_u32 s1, s63, 0
	v_lshlrev_b64 v[146:147], 2, v[0:1]
	v_lshl_add_u64 v[130:131], s[0:1], 0, v[146:147]
	s_mov_b64 s[0:1], 0x1d000
	v_lshl_add_u64 v[132:133], v[130:131], 0, s[0:1]
	s_mov_b32 s0, 0x1d000
	v_add_co_u32_e32 v130, vcc, s0, v130
	v_readlane_b32 s0, v252, 46
	v_readlane_b32 s2, v254, 31
	v_readlane_b32 s3, v254, 32
	v_add_u32_e32 v176, s0, v148
	v_or_b32_e32 v168, 16, v176
	v_ashrrev_i32_e32 v177, 31, v176
	v_ashrrev_i32_e32 v169, 31, v168
	v_lshl_add_u64 v[148:149], s[2:3], 0, v[146:147]
	v_lshlrev_b64 v[150:151], 12, v[176:177]
	v_lshlrev_b64 v[180:181], 12, v[168:169]
	v_addc_co_u32_e32 v131, vcc, 0, v131, vcc
	v_lshl_add_u64 v[164:165], v[148:149], 0, v[150:151]
	v_lshl_add_u64 v[182:183], v[148:149], 0, v[180:181]
	global_load_dwordx4 v[142:145], v[130:131], off
	global_load_dwordx4 v[138:141], v[132:133], off offset:64
	global_load_dwordx4 v[134:137], v[132:133], off offset:512
	s_nop 0
	global_load_dwordx4 v[130:133], v[132:133], off offset:576
	s_nop 0
	global_load_dwordx4 v[152:155], v[164:165], off
	global_load_dwordx4 v[156:159], v[164:165], off offset:64
	global_load_dwordx4 v[160:163], v[164:165], off offset:512
	s_nop 0
	global_load_dwordx4 v[164:167], v[164:165], off offset:576
	s_nop 0
	global_load_dwordx4 v[168:171], v[182:183], off
	global_load_dwordx4 v[172:175], v[182:183], off offset:64
	global_load_dwordx4 v[186:189], v[182:183], off offset:512
	global_load_dwordx4 v[190:193], v[182:183], off offset:576
	v_or_b32_e32 v182, 32, v176
	v_ashrrev_i32_e32 v183, 31, v182
	v_lshlrev_b64 v[182:183], 12, v[182:183]
	v_or_b32_e32 v176, 48, v176
	v_lshl_add_u64 v[184:185], v[148:149], 0, v[182:183]
	v_ashrrev_i32_e32 v177, 31, v176
	global_load_dwordx4 v[198:201], v[184:185], off
	global_load_dwordx4 v[202:205], v[184:185], off offset:64
	global_load_dwordx4 v[206:209], v[184:185], off offset:512
	global_load_dwordx4 v[214:217], v[184:185], off offset:576
	v_lshlrev_b64 v[176:177], 12, v[176:177]
	v_lshl_add_u64 v[184:185], v[148:149], 0, v[176:177]
	global_load_dwordx4 v[218:221], v[184:185], off
	global_load_dwordx4 v[222:225], v[184:185], off offset:64
	global_load_dwordx4 v[226:229], v[184:185], off offset:512
	global_load_dwordx4 v[230:233], v[184:185], off offset:576
	s_mov_b64 s[0:1], 0x80000
	s_cmpk_lt_u32 s20, 0x100
	s_waitcnt vmcnt(0) lgkmcnt(0)
	v_pk_fma_f32 v[126:127], v[126:127], v[142:143], v[152:153]
	v_lshl_add_u64 v[152:153], s[2:3], 0, v[150:151]
	v_lshl_add_u64 v[152:153], v[152:153], 0, v[146:147]
	v_pk_fma_f32 v[116:117], v[116:117], v[132:133], v[166:167]
	v_pk_fma_f32 v[114:115], v[114:115], v[130:131], v[164:165]
	global_store_dwordx4 v[152:153], v[114:117], off offset:576
	v_pk_fma_f32 v[100:101], v[100:101], v[132:133], v[192:193]
	v_pk_fma_f32 v[98:99], v[98:99], v[130:131], v[190:191]
	v_lshl_add_u64 v[114:115], s[2:3], 0, v[180:181]
	v_lshl_add_u64 v[114:115], v[114:115], 0, v[146:147]
	global_store_dwordx4 v[114:115], v[98:101], off offset:576
	v_pk_fma_f32 v[84:85], v[84:85], v[132:133], v[216:217]
	v_pk_fma_f32 v[82:83], v[82:83], v[130:131], v[214:215]
	v_lshl_add_u64 v[98:99], s[2:3], 0, v[182:183]
	v_lshl_add_u64 v[98:99], v[98:99], 0, v[146:147]
	global_store_dwordx4 v[98:99], v[82:85], off offset:576
	v_pk_fma_f32 v[128:129], v[128:129], v[144:145], v[154:155]
	v_pk_fma_f32 v[124:125], v[124:125], v[140:141], v[158:159]
	v_lshl_add_u64 v[82:83], s[2:3], 0, v[176:177]
	v_pk_fma_f32 v[122:123], v[122:123], v[138:139], v[156:157]
	v_pk_fma_f32 v[120:121], v[120:121], v[136:137], v[162:163]
	v_pk_fma_f32 v[118:119], v[118:119], v[134:135], v[160:161]
	v_pk_fma_f32 v[112:113], v[112:113], v[144:145], v[170:171]
	v_pk_fma_f32 v[110:111], v[110:111], v[142:143], v[168:169]
	v_pk_fma_f32 v[108:109], v[108:109], v[140:141], v[174:175]
	v_pk_fma_f32 v[106:107], v[106:107], v[138:139], v[172:173]
	v_pk_fma_f32 v[104:105], v[104:105], v[136:137], v[188:189]
	v_pk_fma_f32 v[102:103], v[102:103], v[134:135], v[186:187]
	v_pk_fma_f32 v[96:97], v[96:97], v[144:145], v[200:201]
	v_pk_fma_f32 v[94:95], v[94:95], v[142:143], v[198:199]
	v_pk_fma_f32 v[92:93], v[92:93], v[140:141], v[204:205]
	v_pk_fma_f32 v[90:91], v[90:91], v[138:139], v[202:203]
	v_pk_fma_f32 v[88:89], v[88:89], v[136:137], v[208:209]
	v_pk_fma_f32 v[86:87], v[86:87], v[134:135], v[206:207]
	v_pk_fma_f32 v[80:81], v[80:81], v[144:145], v[220:221]
	v_pk_fma_f32 v[78:79], v[78:79], v[142:143], v[218:219]
	v_lshl_add_u64 v[82:83], v[82:83], 0, v[146:147]
	v_pk_fma_f32 v[76:77], v[76:77], v[140:141], v[224:225]
	v_pk_fma_f32 v[74:75], v[74:75], v[138:139], v[222:223]
	v_pk_fma_f32 v[72:73], v[72:73], v[136:137], v[228:229]
	v_pk_fma_f32 v[70:71], v[70:71], v[134:135], v[226:227]
	v_pk_fma_f32 v[68:69], v[68:69], v[132:133], v[232:233]
	v_pk_fma_f32 v[66:67], v[66:67], v[130:131], v[230:231]
	v_lshl_add_u64 v[156:157], v[150:151], 0, s[0:1]
	global_store_dwordx4 v[152:153], v[126:129], off
	global_store_dwordx4 v[152:153], v[122:125], off offset:64
; #define PG8_WAIT_V(n) asm volatile("s_waitcnt vmcnt(" #n ")" ::: "memory")
; #define PG8_BAR __builtin_amdgcn_s_barrier()
; template <class Epi, class Sched>
; DI void gemm_phase(LAS unsigned char* lds, const Gemm g, const Sched& S, const Epi& E) {
;     ...
;   PG8_WAIT_V(0);
;   if (wr == 0) PG8_BAR;
;   DI void operator()(const f32x4 (&acc)[2][2][4][2], const Unit& u, int wr, int wc, int fr, int fq) const {
;     ...
;     for (int ai = 0; ai < 2; ++ai) {
;       f32x4 sv[4][2][2];
; #pragma unroll
;       for (int m = 0; m < 4; ++m) {
;         const size_t ro = (size_t)(row0 + ai * HALF + m * 16) * DM + col0;
; #pragma unroll
;         for (int bj = 0; bj < 2; ++bj)
; #pragma unroll
;           for (int n = 0; n < 2; ++n) sv[m][bj][n] = *(const f32x4*)(src + ro + bj * HALF + n * 16);
;       }
; #pragma unroll
;       for (int m = 0; m < 4; ++m) {
;         const size_t ro = (size_t)(row0 + ai * HALF + m * 16) * DM + col0;
; #pragma unroll
;         for (int bj = 0; bj < 2; ++bj)
; #pragma unroll
;           for (int n = 0; n < 2; ++n) *(f32x4*)(dst + ro + bj * HALF + n * 16) = sv[m][bj][n] + gv[bj][n] * acc[ai][bj][m][n];
;       }
	global_store_dwordx4 v[152:153], v[118:121], off offset:512
	global_store_dwordx4 v[114:115], v[110:113], off
	global_store_dwordx4 v[114:115], v[106:109], off offset:64
	global_store_dwordx4 v[114:115], v[102:105], off offset:512
	global_store_dwordx4 v[98:99], v[94:97], off
	global_store_dwordx4 v[98:99], v[90:93], off offset:64
	global_store_dwordx4 v[98:99], v[86:89], off offset:512
	global_store_dwordx4 v[82:83], v[78:81], off
	global_store_dwordx4 v[82:83], v[74:77], off offset:64
	global_store_dwordx4 v[82:83], v[70:73], off offset:512
	global_store_dwordx4 v[82:83], v[66:69], off offset:576
	s_mov_b64 s[0:1], 0x90000
	v_lshl_add_u64 v[152:153], v[150:151], 0, s[0:1]
	v_lshl_add_u64 v[66:67], v[148:149], 0, v[156:157]
	global_load_dwordx4 v[114:117], v[66:67], off
	global_load_dwordx4 v[90:93], v[66:67], off offset:64
	global_load_dwordx4 v[74:77], v[66:67], off offset:512
	s_nop 0
	global_load_dwordx4 v[66:69], v[66:67], off offset:576
	v_lshl_add_u64 v[70:71], v[148:149], 0, v[152:153]
	s_mov_b64 s[0:1], 0xa0000
	global_load_dwordx4 v[126:129], v[70:71], off
	global_load_dwordx4 v[122:125], v[70:71], off offset:64
	global_load_dwordx4 v[118:121], v[70:71], off offset:512
	global_load_dwordx4 v[94:97], v[70:71], off offset:576
	v_lshl_add_u64 v[154:155], v[150:151], 0, s[0:1]
	v_lshl_add_u64 v[70:71], v[148:149], 0, v[154:155]
	s_mov_b64 s[0:1], 0xb0000
	global_load_dwordx4 v[110:113], v[70:71], off
	global_load_dwordx4 v[106:109], v[70:71], off offset:64
	global_load_dwordx4 v[98:101], v[70:71], off offset:512
	global_load_dwordx4 v[102:105], v[70:71], off offset:576
	v_lshl_add_u64 v[150:151], v[150:151], 0, s[0:1]
	v_lshl_add_u64 v[70:71], v[148:149], 0, v[150:151]
	global_load_dwordx4 v[86:89], v[70:71], off
	global_load_dwordx4 v[82:85], v[70:71], off offset:64
	global_load_dwordx4 v[78:81], v[70:71], off offset:512
	s_nop 0
	global_load_dwordx4 v[70:73], v[70:71], off offset:576
	s_waitcnt vmcnt(0) lgkmcnt(0)
	v_pk_fma_f32 v[62:63], v[62:63], v[142:143], v[114:115]
	v_lshl_add_u64 v[114:115], s[2:3], 0, v[156:157]
	v_lshl_add_u64 v[114:115], v[114:115], 0, v[146:147]
	v_pk_fma_f32 v[52:53], v[52:53], v[132:133], v[68:69]
	v_pk_fma_f32 v[50:51], v[50:51], v[130:131], v[66:67]
	global_store_dwordx4 v[114:115], v[50:53], off offset:576
	v_pk_fma_f32 v[36:37], v[36:37], v[132:133], v[96:97]
	v_pk_fma_f32 v[34:35], v[34:35], v[130:131], v[94:95]
	v_lshl_add_u64 v[50:51], s[2:3], 0, v[152:153]
	v_lshl_add_u64 v[50:51], v[50:51], 0, v[146:147]
	global_store_dwordx4 v[50:51], v[34:37], off offset:576
	v_pk_fma_f32 v[20:21], v[20:21], v[132:133], v[104:105]
	v_pk_fma_f32 v[18:19], v[18:19], v[130:131], v[102:103]
	v_lshl_add_u64 v[34:35], s[2:3], 0, v[154:155]
	v_lshl_add_u64 v[34:35], v[34:35], 0, v[146:147]
	global_store_dwordx4 v[34:35], v[18:21], off offset:576
	v_pk_fma_f32 v[64:65], v[64:65], v[144:145], v[116:117]
	v_pk_fma_f32 v[60:61], v[60:61], v[140:141], v[92:93]
	v_lshl_add_u64 v[18:19], s[2:3], 0, v[150:151]
	v_pk_fma_f32 v[58:59], v[58:59], v[138:139], v[90:91]
	v_pk_fma_f32 v[56:57], v[56:57], v[136:137], v[76:77]
	v_pk_fma_f32 v[54:55], v[54:55], v[134:135], v[74:75]
	v_pk_fma_f32 v[48:49], v[48:49], v[144:145], v[128:129]
	v_pk_fma_f32 v[46:47], v[46:47], v[142:143], v[126:127]
	v_pk_fma_f32 v[44:45], v[44:45], v[140:141], v[124:125]
	v_pk_fma_f32 v[42:43], v[42:43], v[138:139], v[122:123]
	v_pk_fma_f32 v[40:41], v[40:41], v[136:137], v[120:121]
	v_pk_fma_f32 v[38:39], v[38:39], v[134:135], v[118:119]
	v_pk_fma_f32 v[32:33], v[32:33], v[144:145], v[112:113]
	v_pk_fma_f32 v[30:31], v[30:31], v[142:143], v[110:111]
	v_pk_fma_f32 v[28:29], v[28:29], v[140:141], v[108:109]
	v_pk_fma_f32 v[26:27], v[26:27], v[138:139], v[106:107]
	v_pk_fma_f32 v[24:25], v[24:25], v[136:137], v[100:101]
	v_pk_fma_f32 v[22:23], v[22:23], v[134:135], v[98:99]
	v_pk_fma_f32 v[16:17], v[16:17], v[144:145], v[88:89]
	v_pk_fma_f32 v[14:15], v[14:15], v[142:143], v[86:87]
	v_lshl_add_u64 v[18:19], v[18:19], 0, v[146:147]
	v_pk_fma_f32 v[12:13], v[12:13], v[140:141], v[84:85]
	v_pk_fma_f32 v[10:11], v[10:11], v[138:139], v[82:83]
	v_pk_fma_f32 v[8:9], v[8:9], v[136:137], v[80:81]
	v_pk_fma_f32 v[6:7], v[6:7], v[134:135], v[78:79]
	v_pk_fma_f32 v[4:5], v[4:5], v[132:133], v[72:73]
	v_pk_fma_f32 v[2:3], v[2:3], v[130:131], v[70:71]
	global_store_dwordx4 v[114:115], v[62:65], off
	global_store_dwordx4 v[114:115], v[58:61], off offset:64
	global_store_dwordx4 v[114:115], v[54:57], off offset:512
	global_store_dwordx4 v[50:51], v[46:49], off
	global_store_dwordx4 v[50:51], v[42:45], off offset:64
	global_store_dwordx4 v[50:51], v[38:41], off offset:512
	global_store_dwordx4 v[34:35], v[30:33], off
	global_store_dwordx4 v[34:35], v[26:29], off offset:64
	global_store_dwordx4 v[34:35], v[22:25], off offset:512
	global_store_dwordx4 v[18:19], v[14:17], off
	global_store_dwordx4 v[18:19], v[10:13], off offset:64
	global_store_dwordx4 v[18:19], v[6:9], off offset:512
	global_store_dwordx4 v[18:19], v[2:5], off offset:576
	s_waitcnt vmcnt(0)
	s_cbranch_scc0 .LBB0_156
	s_barrier

; template <int R>
; DI void norm_rows(const Params& p, int layer, int which, int t0, int tstep, int lane) {
;   const float* g = (which ? p.norm_ffn : p.norm_attn) + layer * DM;
;   const float* md = p.mod + ((size_t)layer * 5 + mb_of(t0)) * 6144 + (which ? 3 * 1024 : 0);
;   float4 v[R][4];
;   float ss[R];
; #pragma unroll
;   for (int r = 0; r < R; ++r) {
;     const float* xr = which ? (const float*)xrow_dst(p, t0 + r * tstep) : xrow_src(p, layer, t0 + r * tstep);
; #pragma unroll
;     for (int j = 0; j < 4; ++j) v[r][j] = *(const float4*)(xr + lane * 4 + 256 * j);
;   }
; #pragma unroll
;   for (int r = 0; r < R; ++r) {
;     ss[r] = 0.f;
; #pragma unroll
;     for (int j = 0; j < 4; ++j) ss[r] += v[r][j].x * v[r][j].x + v[r][j].y * v[r][j].y + v[r][j].z * v[r][j].z + v[r][j].w * v[r][j].w;
;   }
; #pragma unroll
;   for (int o = 32; o >= 1; o >>= 1)
; #pragma unroll
;     for (int r = 0; r < R; ++r) ss[r] += __shfl_xor(ss[r], o);
; #pragma unroll
;   for (int r = 0; r < R; ++r) ss[r] = rsqrtf(ss[r] * (1.f / 1024.f) + EPSV);
;   float4 mm[4], sh[4];
; #pragma unroll
;   for (int j = 0; j < 4; ++j) {
;     int col = lane * 4 + 256 * j;
;     float4 gg = *(const float4*)(g + col);
;     float4 sc = *(const float4*)(md + 1024 + col);
;     sh[j] = *(const float4*)(md + col);
;     mm[j] = make_float4(gg.x * (1.f + sc.x), gg.y * (1.f + sc.y), gg.z * (1.f + sc.z), gg.w * (1.f + sc.w));
;   }
; DI void norm_dyn(const Params& p, int layer, int which, int row0, int row1, unsigned* ctr) {
;     ...
;   while (true) {
;     int ch = grab(ctr);
;     if (ch >= nchunk) break;
;     norm_rows<4>(p, layer, which, row0 + ch * 32 + wid, 8, lane);
.LBB0_201:
	s_or_b64 exec, exec, s[0:1]
	s_waitcnt vmcnt(0) lgkmcnt(0)
	s_barrier
	ds_read_b32 v2, v1
	s_movk_i32 s0, 0x1ff
	s_waitcnt lgkmcnt(0)
	s_barrier
	v_cmp_lt_i32_e32 vcc, s0, v2
	s_mov_b64 s[0:1], -1
	s_cbranch_vccnz .LBB0_196
	v_lshl_add_u32 v54, v2, 5, v106
	s_movk_i32 s0, 0x4000
	v_mov_b64_e32 v[2:3], s[64:65]
	v_mov_b64_e32 v[4:5], s[76:77]
	v_add_u32_e32 v6, 0xffffc000, v54
	v_ashrrev_i32_e32 v55, 31, v54
	v_cmp_gt_i32_e32 vcc, s0, v54
	v_add_u32_e32 v56, 8, v54
	s_movk_i32 s0, 0x3ff8
	v_cndmask_b32_e32 v7, 0, v55, vcc
	v_cndmask_b32_e32 v6, v6, v54, vcc
	v_cndmask_b32_e32 v3, v3, v5, vcc
	v_cndmask_b32_e32 v2, v2, v4, vcc
	v_lshlrev_b64 v[4:5], 12, v[6:7]
	v_lshl_add_u64 v[2:3], v[2:3], 0, v[4:5]
	v_lshl_add_u64 v[2:3], v[2:3], 0, v[0:1]
	v_add_u32_e32 v4, 0xffffc008, v54
	v_ashrrev_i32_e32 v57, 31, v56
	v_cmp_gt_i32_e32 vcc, s0, v54
	v_mov_b64_e32 v[12:13], s[64:65]
	v_mov_b64_e32 v[22:23], s[76:77]
	global_load_dwordx4 v[18:21], v[2:3], off
	global_load_dwordx4 v[14:17], v[2:3], off offset:1024
	v_cndmask_b32_e32 v11, 0, v57, vcc
	v_cndmask_b32_e32 v10, v4, v56, vcc
	global_load_dwordx4 v[6:9], v[2:3], off offset:2048
	s_nop 0
	global_load_dwordx4 v[2:5], v[2:3], off offset:3072
	s_movk_i32 s0, 0x3ff0
	v_lshlrev_b64 v[10:11], 12, v[10:11]
	v_add_u32_e32 v60, 16, v54
	v_add_u32_e32 v24, 0xffffc010, v54
	v_cndmask_b32_e32 v13, v13, v23, vcc
	v_cndmask_b32_e32 v12, v12, v22, vcc
	v_cmp_gt_i32_e64 s[0:1], s0, v54
	v_add_u32_e32 v62, 24, v54
	s_movk_i32 s14, 0x3fe8
	v_lshl_add_u64 v[10:11], v[12:13], 0, v[10:11]
	v_cndmask_b32_e64 v12, v24, v60, s[0:1]
	v_add_u32_e32 v24, 0xffffc018, v54
	v_ashrrev_i32_e32 v63, 31, v62
	v_cmp_gt_i32_e32 vcc, s14, v54
	v_ashrrev_i32_e32 v61, 31, v60
	v_lshl_add_u64 v[10:11], v[10:11], 0, v[0:1]
	v_cndmask_b32_e32 v25, 0, v63, vcc
	v_cndmask_b32_e32 v24, v24, v62, vcc
	v_cndmask_b32_e64 v13, 0, v61, s[0:1]
	v_lshlrev_b64 v[64:65], 12, v[24:25]
	v_mov_b64_e32 v[24:25], s[64:65]
	v_mov_b64_e32 v[26:27], s[76:77]
	global_load_dwordx4 v[46:49], v[10:11], off
	global_load_dwordx4 v[30:33], v[10:11], off offset:1024
	v_lshlrev_b64 v[22:23], 12, v[12:13]
	global_load_dwordx4 v[34:37], v[10:11], off offset:2048
	s_nop 0
	global_load_dwordx4 v[10:13], v[10:11], off offset:3072
	v_min_i32_e32 v40, 0x4000, v54
	v_cndmask_b32_e64 v25, v25, v27, s[0:1]
	v_cndmask_b32_e64 v24, v24, v26, s[0:1]
	v_lshl_add_u64 v[22:23], v[24:25], 0, v[22:23]
	v_lshl_add_u64 v[38:39], v[22:23], 0, v[0:1]
	global_load_dwordx4 v[26:29], v[38:39], off
	global_load_dwordx4 v[22:25], v[38:39], off offset:1024
	v_ashrrev_i32_e32 v40, 12, v40
	v_ashrrev_i32_e32 v41, 31, v40
	v_lshl_add_u64 v[40:41], s[12:13], 0, v[40:41]
	v_mov_b64_e32 v[42:43], s[62:63]
	s_movk_i32 s14, 0x6000
	v_mad_u64_u32 v[42:43], s[0:1], v40, s14, v[42:43]
	v_mad_i32_i24 v43, v41, s14, v43
	v_lshl_add_u64 v[66:67], v[42:43], 0, s[22:23]
	v_lshl_add_u64 v[68:69], v[42:43], 0, s[96:97]
	global_load_dwordx4 v[42:45], v[38:39], off offset:2048
	s_nop 0
	global_load_dwordx4 v[38:41], v[38:39], off offset:3072
	v_lshlrev_b64 v[54:55], 11, v[54:55]
	v_mov_b64_e32 v[50:51], s[76:77]
	v_mov_b64_e32 v[52:53], s[64:65]
	v_lshl_add_u64 v[70:71], v[68:69], 0, v[0:1]
	v_lshl_add_u64 v[90:91], v[76:77], 0, v[54:55]
	v_lshlrev_b64 v[54:55], 11, v[56:57]
	v_lshl_add_u64 v[88:89], v[76:77], 0, v[54:55]
	v_lshlrev_b64 v[54:55], 11, v[60:61]
	global_load_dwordx4 v[108:111], v[70:71], off
	v_mov_b32_e32 v79, v1
	v_lshl_add_u64 v[86:87], v[76:77], 0, v[54:55]
	v_lshlrev_b64 v[54:55], 11, v[62:63]
	global_load_dwordx4 v[112:115], v[74:75], off
	v_lshl_add_u64 v[116:117], v[68:69], 0, v[78:79]
	v_mov_b32_e32 v81, v1
	v_mov_b32_e32 v83, v1
	v_lshl_add_u64 v[72:73], v[66:67], 0, v[0:1]
	v_lshl_add_u64 v[58:59], v[66:67], 0, v[78:79]
	v_lshl_add_u64 v[96:97], v[66:67], 0, v[80:81]
	v_lshl_add_u64 v[92:93], v[66:67], 0, v[82:83]
	v_lshl_add_u64 v[84:85], v[76:77], 0, v[54:55]
	global_load_dwordx4 v[116:119], v[116:117], off
	s_nop 0
	global_load_dwordx4 v[120:123], v[74:75], off offset:1024
	v_lshl_add_u64 v[124:125], v[68:69], 0, v[80:81]
	global_load_dwordx4 v[124:127], v[124:125], off
	s_nop 0
	global_load_dwordx4 v[128:131], v[74:75], off offset:2048
	v_cndmask_b32_e32 v51, v53, v51, vcc
	v_cndmask_b32_e32 v50, v52, v50, vcc
	v_lshl_add_u64 v[50:51], v[50:51], 0, v[64:65]
	v_xor_b32_e32 v64, 16, v211
	v_lshl_add_u64 v[68:69], v[68:69], 0, v[82:83]
	global_load_dwordx4 v[132:135], v[68:69], off
	global_load_dwordx4 v[136:139], v[74:75], off offset:3072
	s_waitcnt vmcnt(0) lgkmcnt(0)
; template <int R>
; DI void norm_rows(const Params& p, int layer, int which, int t0, int tstep, int lane) {
;     ...
; #pragma unroll
;   for (int r = 0; r < R; ++r) {
;     ss[r] = 0.f;
; #pragma unroll
;     for (int j = 0; j < 4; ++j) ss[r] += v[r][j].x * v[r][j].x + v[r][j].y * v[r][j].y + v[r][j].z * v[r][j].z + v[r][j].w * v[r][j].w;
;   }
; #pragma unroll
;   for (int o = 32; o >= 1; o >>= 1)
; #pragma unroll
;     for (int r = 0; r < R; ++r) ss[r] += __shfl_xor(ss[r], o);
; #pragma unroll
;   for (int r = 0; r < R; ++r) ss[r] = rsqrtf(ss[r] * (1.f / 1024.f) + EPSV);
;   float4 mm[4], sh[4];
; #pragma unroll
;   for (int j = 0; j < 4; ++j) {
;     int col = lane * 4 + 256 * j;
;     float4 gg = *(const float4*)(g + col);
;     float4 sc = *(const float4*)(md + 1024 + col);
;     sh[j] = *(const float4*)(md + col);
;     mm[j] = make_float4(gg.x * (1.f + sc.x), gg.y * (1.f + sc.y), gg.z * (1.f + sc.z), gg.w * (1.f + sc.w));
;   }
	v_mov_b32_e32 v62, v19
	v_mov_b32_e32 v63, v15
	v_mov_b32_e32 v60, v18
	v_mov_b32_e32 v61, v14
	v_pk_mul_f32 v[62:63], v[62:63], v[62:63]
	v_mov_b32_e32 v54, v20
	v_mov_b32_e32 v55, v16
	v_pk_fma_f32 v[60:61], v[60:61], v[60:61], v[62:63]
	v_mov_b32_e32 v66, v7
	v_mov_b32_e32 v67, v3
	v_mov_b32_e32 v56, v21
	v_mov_b32_e32 v57, v17
	v_pk_fma_f32 v[54:55], v[54:55], v[54:55], v[60:61]
	v_mov_b32_e32 v62, v6
	v_mov_b32_e32 v63, v2
	v_pk_mul_f32 v[66:67], v[66:67], v[66:67]
	v_pk_fma_f32 v[54:55], v[56:57], v[56:57], v[54:55]
	v_mov_b32_e32 v56, v8
	v_mov_b32_e32 v57, v4
	v_pk_fma_f32 v[62:63], v[62:63], v[62:63], v[66:67]
	v_mov_b32_e32 v60, v9
	v_mov_b32_e32 v61, v5
	v_pk_fma_f32 v[56:57], v[56:57], v[56:57], v[62:63]
	v_xor_b32_e32 v105, 1, v211
	v_pk_fma_f32 v[56:57], v[60:61], v[60:61], v[56:57]
	s_mov_b32 s0, 0x358637bd
	v_mov_b32_e32 v53, v56
	v_mov_b32_e32 v94, v47
	v_mov_b32_e32 v95, v31
	v_mov_b32_e32 v66, v46
	v_mov_b32_e32 v67, v30
	v_pk_mul_f32 v[94:95], v[94:95], v[94:95]
	v_mov_b32_e32 v60, v48
	v_mov_b32_e32 v61, v32
	v_pk_fma_f32 v[66:67], v[66:67], v[66:67], v[94:95]
	v_mov_b32_e32 v98, v35
	v_mov_b32_e32 v99, v11
	v_mov_b32_e32 v62, v49
	v_mov_b32_e32 v63, v33
	v_pk_fma_f32 v[60:61], v[60:61], v[60:61], v[66:67]
	v_mov_b32_e32 v94, v34
	v_mov_b32_e32 v95, v10
	v_pk_mul_f32 v[98:99], v[98:99], v[98:99]
	v_pk_fma_f32 v[60:61], v[62:63], v[62:63], v[60:61]
	v_mov_b32_e32 v62, v36
	v_mov_b32_e32 v63, v12
	v_pk_fma_f32 v[94:95], v[94:95], v[94:95], v[98:99]
	v_mov_b32_e32 v100, v27
	v_mov_b32_e32 v101, v23
	v_mov_b32_e32 v66, v37
	v_mov_b32_e32 v67, v13
	v_pk_fma_f32 v[62:63], v[62:63], v[62:63], v[94:95]
	v_mov_b32_e32 v98, v26
	v_mov_b32_e32 v99, v22
	v_pk_mul_f32 v[100:101], v[100:101], v[100:101]
	v_pk_fma_f32 v[62:63], v[66:67], v[66:67], v[62:63]
	v_mov_b32_e32 v66, v28
	v_mov_b32_e32 v67, v24
	v_pk_fma_f32 v[98:99], v[98:99], v[98:99], v[100:101]
	v_mov_b32_e32 v94, v29
	v_mov_b32_e32 v95, v25
	v_pk_fma_f32 v[66:67], v[66:67], v[66:67], v[98:99]
	v_mov_b32_e32 v52, v62
	v_pk_fma_f32 v[94:95], v[94:95], v[94:95], v[66:67]
	v_lshl_add_u64 v[66:67], v[50:51], 0, v[0:1]
	v_and_b32_e32 v50, 64, v211
	v_add_u32_e32 v79, 64, v50
	v_xor_b32_e32 v50, 32, v211
	v_cmp_lt_i32_e32 vcc, v50, v79
	v_mov_b32_e32 v51, v54
	v_mov_b32_e32 v54, v61
	v_cndmask_b32_e32 v50, v211, v50, vcc
	v_lshlrev_b32_e32 v81, 2, v50
	v_mov_b32_e32 v50, v60
	v_pk_add_f32 v[50:51], v[50:51], v[54:55]
	v_mov_b32_e32 v56, v63
	v_pk_add_f32 v[50:51], v[50:51], v[52:53]
	v_cmp_lt_i32_e32 vcc, v64, v79
	v_pk_add_f32 v[50:51], v[50:51], v[56:57]
	ds_bpermute_b32 v53, v81, v51
	ds_bpermute_b32 v52, v81, v50
	v_cndmask_b32_e32 v60, v211, v64, vcc
	v_lshlrev_b32_e32 v83, 2, v60
	v_xor_b32_e32 v64, 8, v211
	v_cmp_lt_i32_e32 vcc, v64, v79
	s_waitcnt lgkmcnt(0)
	v_pk_add_f32 v[60:61], v[50:51], v[52:53]
	ds_bpermute_b32 v63, v83, v61
	ds_bpermute_b32 v62, v83, v60
	v_cndmask_b32_e32 v50, v211, v64, vcc
	v_lshlrev_b32_e32 v107, 2, v50
	global_load_dwordx4 v[54:57], v[72:73], off
	global_load_dwordx4 v[50:53], v[58:59], off
	s_waitcnt lgkmcnt(0)
	v_pk_add_f32 v[68:69], v[60:61], v[62:63]
	ds_bpermute_b32 v71, v107, v69
	ds_bpermute_b32 v70, v107, v68
	v_xor_b32_e32 v58, 4, v211
	v_cmp_lt_i32_e32 vcc, v58, v79
	v_xor_b32_e32 v72, 2, v211
	v_mov_b32_e32 v104, v43
	v_cndmask_b32_e32 v58, v211, v58, vcc
	v_lshlrev_b32_e32 v145, 2, v58
	s_waitcnt lgkmcnt(0)
	v_pk_add_f32 v[68:69], v[68:69], v[70:71]
	ds_bpermute_b32 v71, v145, v69
	ds_bpermute_b32 v70, v145, v68
	global_load_dwordx4 v[62:65], v[66:67], off
	global_load_dwordx4 v[58:61], v[66:67], off offset:1024
	v_cmp_lt_i32_e32 vcc, v72, v79
	v_mov_b32_e32 v102, v42
	v_mov_b32_e32 v103, v38
	v_cndmask_b32_e32 v72, v211, v72, vcc
	v_lshlrev_b32_e32 v146, 2, v72
	s_waitcnt lgkmcnt(0)
	v_pk_add_f32 v[140:141], v[68:69], v[70:71]
	global_load_dwordx4 v[70:73], v[66:67], off offset:2048
	s_nop 0
	global_load_dwordx4 v[66:69], v[66:67], off offset:3072
	ds_bpermute_b32 v143, v146, v141
	ds_bpermute_b32 v142, v146, v140
	v_cmp_lt_i32_e32 vcc, v105, v79
	v_mov_b32_e32 v100, v44
	v_mov_b32_e32 v101, v40
	v_cndmask_b32_e32 v79, v211, v105, vcc
	v_lshlrev_b32_e32 v79, 2, v79
	s_waitcnt lgkmcnt(0)
	v_pk_add_f32 v[140:141], v[140:141], v[142:143]
	ds_bpermute_b32 v143, v79, v141
	ds_bpermute_b32 v142, v79, v140
	v_mov_b32_e32 v105, v39
	v_pk_mul_f32 v[104:105], v[104:105], v[104:105]
	s_mov_b32 s16, 0x3a800000
	v_pk_fma_f32 v[102:103], v[102:103], v[102:103], v[104:105]
	v_mov_b64_e32 v[104:105], s[0:1]
	v_pk_fma_f32 v[100:101], v[100:101], v[100:101], v[102:103]
	s_waitcnt lgkmcnt(0)
	v_pk_add_f32 v[102:103], v[140:141], v[142:143]
	s_mov_b32 s14, 0x800000
	v_pk_fma_f32 v[102:103], v[102:103], s[16:17], v[104:105] op_sel_hi:[1,0,0]
	v_mov_b32_e32 v98, v45
	v_mul_f32_e32 v140, 0x4b800000, v103
	v_cmp_gt_f32_e32 vcc, s14, v103
	v_mov_b32_e32 v99, v41
	v_cmp_gt_f32_e64 s[0:1], s14, v102
	v_cndmask_b32_e32 v103, v103, v140, vcc
	v_mul_f32_e32 v140, 0x4b800000, v102
	v_rsq_f32_e32 v103, v103
	v_cndmask_b32_e64 v102, v102, v140, s[0:1]
	v_pk_fma_f32 v[140:141], v[98:99], v[98:99], v[100:101]
	v_pk_add_f32 v[100:101], v[108:109], 1.0 op_sel_hi:[1,0]
	v_rsq_f32_e32 v102, v102
	v_pk_mul_f32 v[108:109], v[112:113], v[100:101]
	v_pk_add_f32 v[100:101], v[110:111], 1.0 op_sel_hi:[1,0]
	v_mul_f32_e32 v98, 0x45800000, v103
	v_pk_mul_f32 v[110:111], v[114:115], v[100:101]
	v_pk_add_f32 v[100:101], v[116:117], 1.0 op_sel_hi:[1,0]
	v_cndmask_b32_e32 v142, v103, v98, vcc
	v_pk_mul_f32 v[112:113], v[120:121], v[100:101]
	v_pk_add_f32 v[100:101], v[118:119], 1.0 op_sel_hi:[1,0]
	v_mul_f32_e32 v98, 0x45800000, v102
	v_pk_mul_f32 v[114:115], v[122:123], v[100:101]
	v_pk_add_f32 v[100:101], v[124:125], 1.0 op_sel_hi:[1,0]
	v_cndmask_b32_e64 v144, v102, v98, s[0:1]
	v_pk_mul_f32 v[116:117], v[128:129], v[100:101]
	v_pk_add_f32 v[100:101], v[126:127], 1.0 op_sel_hi:[1,0]
	global_load_dwordx4 v[96:99], v[96:97], off
	v_pk_mul_f32 v[118:119], v[130:131], v[100:101]
	global_load_dwordx4 v[100:103], v[92:93], off
	v_pk_mul_f32 v[18:19], v[18:19], v[142:143] op_sel_hi:[1,0]
	v_pk_mul_f32 v[20:21], v[20:21], v[142:143] op_sel_hi:[1,0]
	v_pk_mul_f32 v[14:15], v[14:15], v[142:143] op_sel_hi:[1,0]
	v_pk_mul_f32 v[16:17], v[16:17], v[142:143] op_sel_hi:[1,0]
	v_pk_mul_f32 v[32:33], v[32:33], v[144:145] op_sel_hi:[1,0]
	v_pk_add_f32 v[92:93], v[132:133], 1.0 op_sel_hi:[1,0]
	v_pk_add_f32 v[120:121], v[134:135], 1.0 op_sel_hi:[1,0]
	v_pk_mul_f32 v[92:93], v[136:137], v[92:93]
	v_pk_mul_f32 v[120:121], v[138:139], v[120:121]
	v_pk_mul_f32 v[2:3], v[2:3], v[142:143] op_sel_hi:[1,0]
	s_waitcnt vmcnt(0)
; template <int R>
; DI void norm_rows(const Params& p, int layer, int which, int t0, int tstep, int lane) {
;     ...
; #pragma unroll
;   for (int r = 0; r < R; ++r) {
;     ss[r] = 0.f;
; #pragma unroll
;     for (int j = 0; j < 4; ++j) ss[r] += v[r][j].x * v[r][j].x + v[r][j].y * v[r][j].y + v[r][j].z * v[r][j].z + v[r][j].w * v[r][j].w;
;   }
; #pragma unroll
;   for (int o = 32; o >= 1; o >>= 1)
; #pragma unroll
;     for (int r = 0; r < R; ++r) ss[r] += __shfl_xor(ss[r], o);
; #pragma unroll
;   for (int r = 0; r < R; ++r) ss[r] = rsqrtf(ss[r] * (1.f / 1024.f) + EPSV);
;   float4 mm[4], sh[4];
; #pragma unroll
;   for (int j = 0; j < 4; ++j) {
;     int col = lane * 4 + 256 * j;
;     float4 gg = *(const float4*)(g + col);
;     float4 sc = *(const float4*)(md + 1024 + col);
;     sh[j] = *(const float4*)(md + col);
;     mm[j] = make_float4(gg.x * (1.f + sc.x), gg.y * (1.f + sc.y), gg.z * (1.f + sc.z), gg.w * (1.f + sc.w));
;   }
; #pragma unroll
;   for (int j = 0; j < 4; ++j) {
;     int col = lane * 4 + 256 * j;
; #pragma unroll
;     for (int r = 0; r < R; ++r)
;       *(uint2*)(p.H + (size_t)(t0 + r * tstep) * LDK + col) =
;           make_uint2(pack_bf16(v[r][j].x * ss[r] * mm[j].x + sh[j].x, v[r][j].y * ss[r] * mm[j].y + sh[j].y),
;                      pack_bf16(v[r][j].z * ss[r] * mm[j].z + sh[j].z, v[r][j].w * ss[r] * mm[j].w + sh[j].w));
	v_pk_fma_f32 v[18:19], v[18:19], v[108:109], v[54:55]
	v_pk_fma_f32 v[20:21], v[20:21], v[110:111], v[56:57]
	v_cvt_pk_bf16_f32 v18, v18, v19
	v_cvt_pk_bf16_f32 v19, v20, v21
	v_pk_mul_f32 v[20:21], v[46:47], v[144:145] op_sel_hi:[1,0]
	v_pk_mul_f32 v[46:47], v[48:49], v[144:145] op_sel_hi:[1,0]
	v_pk_fma_f32 v[14:15], v[14:15], v[112:113], v[50:51]
	v_pk_fma_f32 v[16:17], v[16:17], v[114:115], v[52:53]
	v_pk_fma_f32 v[20:21], v[108:109], v[20:21], v[54:55]
	v_pk_fma_f32 v[46:47], v[46:47], v[110:111], v[56:57]
	v_cvt_pk_bf16_f32 v14, v14, v15
	v_cvt_pk_bf16_f32 v15, v16, v17
	v_pk_mul_f32 v[16:17], v[30:31], v[144:145] op_sel_hi:[1,0]
	v_mov_b32_e32 v122, v63
	v_mov_b32_e32 v123, v59
	v_mov_b32_e32 v48, v62
	v_mov_b32_e32 v49, v58
	v_pk_mul_f32 v[122:123], v[122:123], v[122:123]
	v_mov_b32_e32 v30, v64
	v_mov_b32_e32 v31, v60
	v_pk_fma_f32 v[48:49], v[48:49], v[48:49], v[122:123]
	v_mov_b32_e32 v124, v71
	v_mov_b32_e32 v125, v67
	v_cvt_pk_bf16_f32 v20, v20, v21
	v_cvt_pk_bf16_f32 v21, v46, v47
	v_mov_b32_e32 v46, v65
	v_mov_b32_e32 v47, v61
	v_pk_fma_f32 v[30:31], v[30:31], v[30:31], v[48:49]
	v_mov_b32_e32 v122, v70
	v_mov_b32_e32 v123, v66
	v_pk_mul_f32 v[124:125], v[124:125], v[124:125]
	v_pk_fma_f32 v[30:31], v[46:47], v[46:47], v[30:31]
	v_mov_b32_e32 v46, v72
	v_mov_b32_e32 v47, v68
	v_pk_fma_f32 v[122:123], v[122:123], v[122:123], v[124:125]
	v_mov_b32_e32 v48, v73
	v_mov_b32_e32 v49, v69
	v_pk_fma_f32 v[46:47], v[46:47], v[46:47], v[122:123]
	v_pk_fma_f32 v[16:17], v[16:17], v[112:113], v[50:51]
	v_pk_fma_f32 v[46:47], v[48:49], v[48:49], v[46:47]
	v_mov_b32_e32 v48, v30
	v_mov_b32_e32 v49, v94
	v_mov_b32_e32 v94, v31
	v_pk_add_f32 v[30:31], v[48:49], v[94:95]
	v_mov_b32_e32 v48, v46
	v_mov_b32_e32 v49, v140
	v_pk_add_f32 v[30:31], v[30:31], v[48:49]
	v_mov_b32_e32 v140, v47
	v_pk_add_f32 v[30:31], v[30:31], v[140:141]
	ds_bpermute_b32 v47, v81, v31
	ds_bpermute_b32 v46, v81, v30
	v_pk_fma_f32 v[32:33], v[32:33], v[114:115], v[52:53]
	v_cvt_pk_bf16_f32 v16, v16, v17
	v_cvt_pk_bf16_f32 v17, v32, v33
	v_pk_mul_f32 v[4:5], v[4:5], v[142:143] op_sel_hi:[1,0]
	s_waitcnt lgkmcnt(0)
	v_pk_add_f32 v[30:31], v[30:31], v[46:47]
	ds_bpermute_b32 v33, v83, v31
	ds_bpermute_b32 v32, v83, v30
	v_pk_mul_f32 v[12:13], v[12:13], v[144:145] op_sel_hi:[1,0]
	v_pk_mul_f32 v[6:7], v[6:7], v[142:143] op_sel_hi:[1,0]
	v_pk_mul_f32 v[8:9], v[8:9], v[142:143] op_sel_hi:[1,0]
	s_mov_b64 s[0:1], 0
	s_waitcnt lgkmcnt(0)
	v_pk_add_f32 v[30:31], v[30:31], v[32:33]
	ds_bpermute_b32 v33, v107, v31
	ds_bpermute_b32 v32, v107, v30
	v_pk_fma_f32 v[6:7], v[6:7], v[116:117], v[96:97]
	v_pk_fma_f32 v[8:9], v[8:9], v[118:119], v[98:99]
	s_waitcnt lgkmcnt(0)
	v_pk_add_f32 v[30:31], v[30:31], v[32:33]
	ds_bpermute_b32 v33, v145, v31
	ds_bpermute_b32 v32, v145, v30
	v_pk_fma_f32 v[2:3], v[2:3], v[92:93], v[100:101]
	v_pk_fma_f32 v[4:5], v[4:5], v[120:121], v[102:103]
	v_cvt_pk_bf16_f32 v2, v2, v3
	v_cvt_pk_bf16_f32 v3, v4, v5
	s_waitcnt lgkmcnt(0)
	v_pk_add_f32 v[30:31], v[30:31], v[32:33]
	ds_bpermute_b32 v33, v146, v31
	ds_bpermute_b32 v32, v146, v30
	v_pk_mul_f32 v[4:5], v[10:11], v[144:145] op_sel_hi:[1,0]
	v_pk_fma_f32 v[12:13], v[12:13], v[120:121], v[102:103]
	v_pk_fma_f32 v[4:5], v[4:5], v[92:93], v[100:101]
	v_cvt_pk_bf16_f32 v6, v6, v7
	s_waitcnt lgkmcnt(0)
	v_pk_add_f32 v[30:31], v[30:31], v[32:33]
	ds_bpermute_b32 v33, v79, v31
	ds_bpermute_b32 v32, v79, v30
	v_cvt_pk_bf16_f32 v4, v4, v5
	v_cvt_pk_bf16_f32 v7, v8, v9
	v_pk_mul_f32 v[8:9], v[34:35], v[144:145] op_sel_hi:[1,0]
	v_pk_mul_f32 v[34:35], v[36:37], v[144:145] op_sel_hi:[1,0]
	s_waitcnt lgkmcnt(0)
; template <int R>
; DI void norm_rows(const Params& p, int layer, int which, int t0, int tstep, int lane) {
;     ...
;   for (int r = 0; r < R; ++r) ss[r] = rsqrtf(ss[r] * (1.f / 1024.f) + EPSV);
;   float4 mm[4], sh[4];
; #pragma unroll
;   for (int j = 0; j < 4; ++j) {
;     int col = lane * 4 + 256 * j;
;     float4 gg = *(const float4*)(g + col);
;     float4 sc = *(const float4*)(md + 1024 + col);
;     sh[j] = *(const float4*)(md + col);
;     mm[j] = make_float4(gg.x * (1.f + sc.x), gg.y * (1.f + sc.y), gg.z * (1.f + sc.z), gg.w * (1.f + sc.w));
;   }
; #pragma unroll
;   for (int j = 0; j < 4; ++j) {
;     int col = lane * 4 + 256 * j;
; #pragma unroll
;     for (int r = 0; r < R; ++r)
;       *(uint2*)(p.H + (size_t)(t0 + r * tstep) * LDK + col) =
;           make_uint2(pack_bf16(v[r][j].x * ss[r] * mm[j].x + sh[j].x, v[r][j].y * ss[r] * mm[j].y + sh[j].y),
;                      pack_bf16(v[r][j].z * ss[r] * mm[j].z + sh[j].z, v[r][j].w * ss[r] * mm[j].w + sh[j].w));
;   }
	v_pk_add_f32 v[10:11], v[30:31], v[32:33]
	v_pk_fma_f32 v[8:9], v[8:9], v[116:117], v[96:97]
	v_pk_fma_f32 v[10:11], v[10:11], s[16:17], v[104:105] op_sel_hi:[1,0,0]
	v_pk_fma_f32 v[34:35], v[34:35], v[118:119], v[98:99]
	v_mul_f32_e32 v5, 0x4b800000, v11
	v_cmp_gt_f32_e32 vcc, s14, v11
	v_cvt_pk_bf16_f32 v8, v8, v9
	v_cvt_pk_bf16_f32 v9, v34, v35
	v_cndmask_b32_e32 v5, v11, v5, vcc
	v_rsq_f32_e32 v11, v5
	v_cvt_pk_bf16_f32 v5, v12, v13
	v_mul_f32_e32 v12, 0x45800000, v11
	v_cndmask_b32_e32 v12, v11, v12, vcc
	v_pk_mul_f32 v[26:27], v[26:27], v[12:13] op_sel_hi:[1,0]
	v_pk_mul_f32 v[28:29], v[28:29], v[12:13] op_sel_hi:[1,0]
	v_pk_mul_f32 v[22:23], v[22:23], v[12:13] op_sel_hi:[1,0]
	v_pk_mul_f32 v[24:25], v[24:25], v[12:13] op_sel_hi:[1,0]
	v_pk_fma_f32 v[26:27], v[108:109], v[26:27], v[54:55]
	v_pk_fma_f32 v[28:29], v[28:29], v[110:111], v[56:57]
	v_pk_fma_f32 v[22:23], v[22:23], v[112:113], v[50:51]
	v_pk_fma_f32 v[24:25], v[24:25], v[114:115], v[52:53]
	v_cvt_pk_bf16_f32 v26, v26, v27
	v_cvt_pk_bf16_f32 v27, v28, v29
	v_cvt_pk_bf16_f32 v22, v22, v23
	v_cvt_pk_bf16_f32 v23, v24, v25
	v_pk_mul_f32 v[24:25], v[42:43], v[12:13] op_sel_hi:[1,0]
	v_pk_mul_f32 v[28:29], v[44:45], v[12:13] op_sel_hi:[1,0]
	v_mul_f32_e32 v11, 0x4b800000, v10
	v_cmp_gt_f32_e32 vcc, s14, v10
	v_pk_fma_f32 v[24:25], v[24:25], v[116:117], v[96:97]
	v_pk_fma_f32 v[28:29], v[28:29], v[118:119], v[98:99]
	v_cndmask_b32_e32 v10, v10, v11, vcc
	v_cvt_pk_bf16_f32 v24, v24, v25
	v_cvt_pk_bf16_f32 v25, v28, v29
	v_pk_mul_f32 v[28:29], v[38:39], v[12:13] op_sel_hi:[1,0]
	v_rsq_f32_e32 v13, v10
	v_pk_fma_f32 v[28:29], v[28:29], v[92:93], v[100:101]
	global_store_dwordx2 v[90:91], v[18:19], off
	global_store_dwordx2 v[88:89], v[20:21], off
	global_store_dwordx2 v[86:87], v[26:27], off
	v_cvt_pk_bf16_f32 v28, v28, v29
	v_pk_mul_f32 v[10:11], v[40:41], v[12:13] op_sel_hi:[1,0]
	s_nop 0
	v_pk_fma_f32 v[10:11], v[10:11], v[120:121], v[102:103]
	s_nop 0
	v_cvt_pk_bf16_f32 v29, v10, v11
	v_mul_f32_e32 v10, 0x45800000, v13
	v_cndmask_b32_e32 v10, v13, v10, vcc
	v_pk_mul_f32 v[12:13], v[62:63], v[10:11] op_sel_hi:[1,0]
	v_pk_mul_f32 v[18:19], v[64:65], v[10:11] op_sel_hi:[1,0]
	v_pk_fma_f32 v[12:13], v[108:109], v[12:13], v[54:55]
	v_pk_fma_f32 v[18:19], v[110:111], v[18:19], v[56:57]
	v_cvt_pk_bf16_f32 v12, v12, v13
	v_cvt_pk_bf16_f32 v13, v18, v19
	global_store_dwordx2 v[84:85], v[12:13], off
	global_store_dwordx2 v[90:91], v[14:15], off offset:512
	global_store_dwordx2 v[88:89], v[16:17], off offset:512
	global_store_dwordx2 v[86:87], v[22:23], off offset:512
	v_pk_mul_f32 v[12:13], v[58:59], v[10:11] op_sel_hi:[1,0]
	v_pk_mul_f32 v[14:15], v[60:61], v[10:11] op_sel_hi:[1,0]
	v_pk_fma_f32 v[12:13], v[12:13], v[112:113], v[50:51]
	v_pk_fma_f32 v[14:15], v[14:15], v[114:115], v[52:53]
	v_cvt_pk_bf16_f32 v12, v12, v13
	v_cvt_pk_bf16_f32 v13, v14, v15
	global_store_dwordx2 v[84:85], v[12:13], off offset:512
	global_store_dwordx2 v[90:91], v[6:7], off offset:1024
	global_store_dwordx2 v[88:89], v[8:9], off offset:1024
	global_store_dwordx2 v[86:87], v[24:25], off offset:1024
	v_pk_mul_f32 v[6:7], v[70:71], v[10:11] op_sel_hi:[1,0]
	v_pk_mul_f32 v[8:9], v[72:73], v[10:11] op_sel_hi:[1,0]
	v_pk_fma_f32 v[6:7], v[6:7], v[116:117], v[96:97]
	v_pk_fma_f32 v[8:9], v[8:9], v[118:119], v[98:99]
	v_cvt_pk_bf16_f32 v6, v6, v7
	v_cvt_pk_bf16_f32 v7, v8, v9
	global_store_dwordx2 v[84:85], v[6:7], off offset:1024
	global_store_dwordx2 v[90:91], v[2:3], off offset:1536
	global_store_dwordx2 v[88:89], v[4:5], off offset:1536
	global_store_dwordx2 v[86:87], v[28:29], off offset:1536
	v_pk_mul_f32 v[2:3], v[66:67], v[10:11] op_sel_hi:[1,0]
	v_pk_mul_f32 v[4:5], v[68:69], v[10:11] op_sel_hi:[1,0]
	v_pk_fma_f32 v[2:3], v[2:3], v[92:93], v[100:101]
	v_pk_fma_f32 v[4:5], v[4:5], v[120:121], v[102:103]
	v_cvt_pk_bf16_f32 v2, v2, v3
	v_cvt_pk_bf16_f32 v3, v4, v5
	global_store_dwordx2 v[84:85], v[2:3], off offset:1536
	s_branch .LBB0_196

;   DI void operator()(const f32x4 (&acc)[2][2][4][2], const Unit& u, int wr, int wc, int fr, int fq) const {
;     asm volatile("" ::: "memory");
;     const int row0 = u.pm * BM + wr * 64 + fr, col0 = u.pn * BM + wc * 32 + 4 * fq;
;     f32x4 gv[2][2];
; #pragma unroll
;     for (int bj = 0; bj < 2; ++bj)
; #pragma unroll
;       for (int n = 0; n < 2; ++n) gv[bj][n] = *(const f32x4*)(gate + col0 + bj * HALF + n * 16);
; #pragma unroll
;     for (int ai = 0; ai < 2; ++ai) {
;       f32x4 sv[4][2][2];
; #pragma unroll
;       for (int m = 0; m < 4; ++m) {
;         const size_t ro = (size_t)(row0 + ai * HALF + m * 16) * DM + col0;
; #pragma unroll
;         for (int bj = 0; bj < 2; ++bj)
; #pragma unroll
;           for (int n = 0; n < 2; ++n) sv[m][bj][n] = *(const f32x4*)(src + ro + bj * HALF + n * 16);
;       }
; #pragma unroll
;       for (int m = 0; m < 4; ++m) {
;         const size_t ro = (size_t)(row0 + ai * HALF + m * 16) * DM + col0;
; #pragma unroll
;         for (int bj = 0; bj < 2; ++bj)
; #pragma unroll
;           for (int n = 0; n < 2; ++n) *(f32x4*)(dst + ro + bj * HALF + n * 16) = sv[m][bj][n] + gv[bj][n] * acc[ai][bj][m][n];
;       }
.LBB0_218:
	s_ashr_i32 s10, s2, 4
	v_readlane_b32 s12, v254, 33
	s_lshl_b32 s3, s26, 8
	s_ashr_i32 s11, s10, 31
	s_mov_b32 s14, s12
	s_mul_i32 s12, s12, 5
	s_add_u32 s10, s12, s10
	s_mul_hi_u32 s12, s14, 5
	s_addc_u32 s11, s12, s11
	s_mulk_i32 s11, 0x6000
	s_mul_hi_u32 s12, s10, 0x6000
	v_lshl_or_b32 v0, v136, 2, s3
	s_add_i32 s12, s12, s11
	s_mulk_i32 s10, 0x6000
	v_or_b32_e32 v130, s27, v0
	s_add_u32 s10, s62, s10
	v_ashrrev_i32_e32 v131, 31, v130
	s_addc_u32 s11, s63, s12
	v_lshlrev_b64 v[174:175], 2, v[130:131]
	v_lshl_add_u32 v146, s2, 8, v146
	v_lshl_add_u64 v[130:131], s[10:11], 0, v[174:175]
	s_mov_b64 s[10:11], 0x2000
	s_movk_i32 s3, 0x2000
	v_ashrrev_i32_e32 v147, 31, v146
	v_lshl_add_u64 v[132:133], v[130:131], 0, s[10:11]
	v_add_co_u32_e32 v130, vcc, s3, v130
	v_lshl_add_u64 v[176:177], s[0:1], 0, v[174:175]
	v_lshlrev_b64 v[186:187], 12, v[146:147]
	v_addc_co_u32_e32 v131, vcc, 0, v131, vcc
	v_lshl_add_u64 v[148:149], v[176:177], 0, v[186:187]
	global_load_dwordx4 v[142:145], v[130:131], off
	global_load_dwordx4 v[138:141], v[132:133], off offset:64
	global_load_dwordx4 v[134:137], v[132:133], off offset:512
	s_nop 0
	global_load_dwordx4 v[130:133], v[132:133], off offset:576
	s_nop 0
	global_load_dwordx4 v[198:201], v[148:149], off
	global_load_dwordx4 v[202:205], v[148:149], off offset:64
	global_load_dwordx4 v[206:209], v[148:149], off offset:512
	global_load_dwordx4 v[214:217], v[148:149], off offset:576
	v_or_b32_e32 v148, 16, v146
	v_ashrrev_i32_e32 v149, 31, v148
	v_lshlrev_b64 v[180:181], 12, v[148:149]
	v_lshl_add_u64 v[148:149], v[176:177], 0, v[180:181]
	global_load_dwordx4 v[218:221], v[148:149], off
	global_load_dwordx4 v[222:225], v[148:149], off offset:64
	global_load_dwordx4 v[226:229], v[148:149], off offset:512
	global_load_dwordx4 v[230:233], v[148:149], off offset:576
	v_or_b32_e32 v148, 32, v146
	v_ashrrev_i32_e32 v149, 31, v148
	v_lshlrev_b64 v[190:191], 12, v[148:149]
	v_or_b32_e32 v146, 48, v146
	v_lshl_add_u64 v[148:149], v[176:177], 0, v[190:191]
	v_ashrrev_i32_e32 v147, 31, v146
	global_load_dwordx4 v[234:237], v[148:149], off
	global_load_dwordx4 v[170:173], v[148:149], off offset:64
	global_load_dwordx4 v[166:169], v[148:149], off offset:512
	global_load_dwordx4 v[162:165], v[148:149], off offset:576
	v_lshlrev_b64 v[188:189], 12, v[146:147]
	v_lshl_add_u64 v[146:147], v[176:177], 0, v[188:189]
	global_load_dwordx4 v[158:161], v[146:147], off
	global_load_dwordx4 v[154:157], v[146:147], off offset:64
	global_load_dwordx4 v[150:153], v[146:147], off offset:512
	s_nop 0
	global_load_dwordx4 v[146:149], v[146:147], off offset:576
	v_lshl_add_u64 v[182:183], s[8:9], 0, v[186:187]
	v_lshl_add_u64 v[182:183], v[182:183], 0, v[174:175]
	s_mov_b64 s[2:3], 0x80000
	s_cmpk_lt_u32 s25, 0x100
	v_readlane_b32 s13, v254, 34
	s_waitcnt vmcnt(0) lgkmcnt(0)
	v_pk_fma_f32 v[128:129], v[128:129], v[144:145], v[200:201]
	v_pk_fma_f32 v[126:127], v[126:127], v[142:143], v[198:199]
	global_store_dwordx4 v[182:183], v[126:129], off
	v_pk_fma_f32 v[116:117], v[116:117], v[132:133], v[216:217]
	v_pk_fma_f32 v[114:115], v[114:115], v[130:131], v[214:215]
	global_store_dwordx4 v[182:183], v[114:117], off offset:576
	v_pk_fma_f32 v[124:125], v[124:125], v[140:141], v[204:205]
	v_pk_fma_f32 v[122:123], v[122:123], v[138:139], v[202:203]
	v_lshl_add_u64 v[114:115], s[8:9], 0, v[180:181]
	v_lshl_add_u64 v[114:115], v[114:115], 0, v[174:175]
	v_pk_fma_f32 v[100:101], v[100:101], v[132:133], v[232:233]
	v_pk_fma_f32 v[98:99], v[98:99], v[130:131], v[230:231]
	global_store_dwordx4 v[114:115], v[98:101], off offset:576
	v_pk_fma_f32 v[120:121], v[120:121], v[136:137], v[208:209]
	v_pk_fma_f32 v[118:119], v[118:119], v[134:135], v[206:207]
	v_lshl_add_u64 v[98:99], s[8:9], 0, v[190:191]
	v_lshl_add_u64 v[98:99], v[98:99], 0, v[174:175]
	v_pk_fma_f32 v[84:85], v[84:85], v[132:133], v[164:165]
	v_pk_fma_f32 v[82:83], v[82:83], v[130:131], v[162:163]
	global_store_dwordx4 v[98:99], v[82:85], off offset:576
	v_pk_fma_f32 v[112:113], v[112:113], v[144:145], v[220:221]
	v_pk_fma_f32 v[110:111], v[110:111], v[142:143], v[218:219]
	v_lshl_add_u64 v[82:83], s[8:9], 0, v[188:189]
	v_pk_fma_f32 v[108:109], v[108:109], v[140:141], v[224:225]
	v_pk_fma_f32 v[106:107], v[106:107], v[138:139], v[222:223]
	v_pk_fma_f32 v[104:105], v[104:105], v[136:137], v[228:229]
	v_pk_fma_f32 v[102:103], v[102:103], v[134:135], v[226:227]
	v_pk_fma_f32 v[96:97], v[96:97], v[144:145], v[236:237]
	v_pk_fma_f32 v[94:95], v[94:95], v[142:143], v[234:235]
	v_pk_fma_f32 v[92:93], v[92:93], v[140:141], v[172:173]
	v_pk_fma_f32 v[90:91], v[90:91], v[138:139], v[170:171]
	v_pk_fma_f32 v[88:89], v[88:89], v[136:137], v[168:169]
	v_pk_fma_f32 v[86:87], v[86:87], v[134:135], v[166:167]
	v_pk_fma_f32 v[80:81], v[80:81], v[144:145], v[160:161]
	v_pk_fma_f32 v[78:79], v[78:79], v[142:143], v[158:159]
	v_lshl_add_u64 v[82:83], v[82:83], 0, v[174:175]
	v_pk_fma_f32 v[76:77], v[76:77], v[140:141], v[156:157]
	v_pk_fma_f32 v[74:75], v[74:75], v[138:139], v[154:155]
	v_pk_fma_f32 v[72:73], v[72:73], v[136:137], v[152:153]
	v_pk_fma_f32 v[70:71], v[70:71], v[134:135], v[150:151]
	v_pk_fma_f32 v[68:69], v[68:69], v[132:133], v[148:149]
; #define PG8_WAIT_V(n) asm volatile("s_waitcnt vmcnt(" #n ")" ::: "memory")
; #define PG8_BAR __builtin_amdgcn_s_barrier()
; template <class Epi, class Sched>
; DI void gemm_phase(LAS unsigned char* lds, const Gemm g, const Sched& S, const Epi& E) {
;     ...
;   PG8_WAIT_V(0);
;   if (wr == 0) PG8_BAR;
;   DI void operator()(const f32x4 (&acc)[2][2][4][2], const Unit& u, int wr, int wc, int fr, int fq) const {
;     ...
;     for (int ai = 0; ai < 2; ++ai) {
;       f32x4 sv[4][2][2];
; #pragma unroll
;       for (int m = 0; m < 4; ++m) {
;         const size_t ro = (size_t)(row0 + ai * HALF + m * 16) * DM + col0;
; #pragma unroll
;         for (int bj = 0; bj < 2; ++bj)
; #pragma unroll
;           for (int n = 0; n < 2; ++n) sv[m][bj][n] = *(const f32x4*)(src + ro + bj * HALF + n * 16);
;       }
; #pragma unroll
;       for (int m = 0; m < 4; ++m) {
;         const size_t ro = (size_t)(row0 + ai * HALF + m * 16) * DM + col0;
; #pragma unroll
;         for (int bj = 0; bj < 2; ++bj)
; #pragma unroll
;           for (int n = 0; n < 2; ++n) *(f32x4*)(dst + ro + bj * HALF + n * 16) = sv[m][bj][n] + gv[bj][n] * acc[ai][bj][m][n];
;       }
	v_pk_fma_f32 v[66:67], v[66:67], v[130:131], v[146:147]
	v_lshl_add_u64 v[128:129], v[186:187], 0, s[2:3]
	global_store_dwordx4 v[182:183], v[122:125], off offset:64
	global_store_dwordx4 v[182:183], v[118:121], off offset:512
	global_store_dwordx4 v[114:115], v[110:113], off
	global_store_dwordx4 v[114:115], v[106:109], off offset:64
	global_store_dwordx4 v[114:115], v[102:105], off offset:512
	global_store_dwordx4 v[98:99], v[94:97], off
	global_store_dwordx4 v[98:99], v[90:93], off offset:64
	global_store_dwordx4 v[98:99], v[86:89], off offset:512
	global_store_dwordx4 v[82:83], v[78:81], off
	global_store_dwordx4 v[82:83], v[74:77], off offset:64
	global_store_dwordx4 v[82:83], v[70:73], off offset:512
	global_store_dwordx4 v[82:83], v[66:69], off offset:576
	s_mov_b64 s[2:3], 0x90000
	v_lshl_add_u64 v[150:151], v[186:187], 0, s[2:3]
	v_lshl_add_u64 v[66:67], v[176:177], 0, v[128:129]
	global_load_dwordx4 v[96:99], v[66:67], off
	global_load_dwordx4 v[100:103], v[66:67], off offset:64
	global_load_dwordx4 v[104:107], v[66:67], off offset:512
	global_load_dwordx4 v[108:111], v[66:67], off offset:576
	v_lshl_add_u64 v[66:67], v[176:177], 0, v[150:151]
	s_mov_b64 s[2:3], 0xa0000
	global_load_dwordx4 v[112:115], v[66:67], off
	global_load_dwordx4 v[116:119], v[66:67], off offset:64
	global_load_dwordx4 v[120:123], v[66:67], off offset:512
	global_load_dwordx4 v[124:127], v[66:67], off offset:576
	v_lshl_add_u64 v[152:153], v[186:187], 0, s[2:3]
	v_lshl_add_u64 v[66:67], v[176:177], 0, v[152:153]
	s_mov_b64 s[2:3], 0xb0000
	global_load_dwordx4 v[146:149], v[66:67], off
	global_load_dwordx4 v[90:93], v[66:67], off offset:64
	global_load_dwordx4 v[86:89], v[66:67], off offset:512
	global_load_dwordx4 v[82:85], v[66:67], off offset:576
	v_lshl_add_u64 v[94:95], v[186:187], 0, s[2:3]
	v_lshl_add_u64 v[66:67], v[176:177], 0, v[94:95]
	global_load_dwordx4 v[78:81], v[66:67], off
	global_load_dwordx4 v[74:77], v[66:67], off offset:64
	global_load_dwordx4 v[70:73], v[66:67], off offset:512
	s_nop 0
	global_load_dwordx4 v[66:69], v[66:67], off offset:576
	s_waitcnt vmcnt(0) lgkmcnt(0)
	v_pk_fma_f32 v[62:63], v[62:63], v[142:143], v[96:97]
	v_lshl_add_u64 v[96:97], s[8:9], 0, v[128:129]
	v_lshl_add_u64 v[96:97], v[96:97], 0, v[174:175]
	v_pk_fma_f32 v[48:49], v[48:49], v[132:133], v[110:111]
	v_pk_fma_f32 v[46:47], v[46:47], v[130:131], v[108:109]
	global_store_dwordx4 v[96:97], v[46:49], off offset:576
	v_pk_fma_f32 v[32:33], v[32:33], v[132:133], v[126:127]
	v_pk_fma_f32 v[30:31], v[30:31], v[130:131], v[124:125]
	v_pk_fma_f32 v[46:47], v[50:51], v[142:143], v[112:113]
	v_lshl_add_u64 v[50:51], s[8:9], 0, v[150:151]
	v_lshl_add_u64 v[50:51], v[50:51], 0, v[174:175]
	global_store_dwordx4 v[50:51], v[30:33], off offset:576
	v_pk_fma_f32 v[20:21], v[20:21], v[132:133], v[84:85]
	v_pk_fma_f32 v[18:19], v[18:19], v[130:131], v[82:83]
	v_pk_fma_f32 v[30:31], v[34:35], v[142:143], v[146:147]
	v_lshl_add_u64 v[34:35], s[8:9], 0, v[152:153]
	v_lshl_add_u64 v[34:35], v[34:35], 0, v[174:175]
	global_store_dwordx4 v[34:35], v[18:21], off offset:576
	v_pk_fma_f32 v[64:65], v[64:65], v[144:145], v[98:99]
	v_pk_fma_f32 v[60:61], v[60:61], v[140:141], v[102:103]
	v_lshl_add_u64 v[18:19], s[8:9], 0, v[94:95]
	v_pk_fma_f32 v[58:59], v[58:59], v[138:139], v[100:101]
	v_pk_fma_f32 v[56:57], v[56:57], v[136:137], v[106:107]
	v_pk_fma_f32 v[54:55], v[54:55], v[134:135], v[104:105]
	v_pk_fma_f32 v[48:49], v[52:53], v[144:145], v[114:115]
	v_pk_fma_f32 v[44:45], v[44:45], v[140:141], v[118:119]
	v_pk_fma_f32 v[42:43], v[42:43], v[138:139], v[116:117]
	v_pk_fma_f32 v[40:41], v[40:41], v[136:137], v[122:123]
	v_pk_fma_f32 v[38:39], v[38:39], v[134:135], v[120:121]
	v_pk_fma_f32 v[32:33], v[36:37], v[144:145], v[148:149]
	v_pk_fma_f32 v[28:29], v[28:29], v[140:141], v[92:93]
	v_pk_fma_f32 v[26:27], v[26:27], v[138:139], v[90:91]
	v_pk_fma_f32 v[24:25], v[24:25], v[136:137], v[88:89]
	v_pk_fma_f32 v[22:23], v[22:23], v[134:135], v[86:87]
	v_pk_fma_f32 v[16:17], v[16:17], v[144:145], v[80:81]
	v_pk_fma_f32 v[14:15], v[14:15], v[142:143], v[78:79]
	v_lshl_add_u64 v[18:19], v[18:19], 0, v[174:175]
	v_pk_fma_f32 v[12:13], v[12:13], v[140:141], v[76:77]
	v_pk_fma_f32 v[10:11], v[10:11], v[138:139], v[74:75]
	v_pk_fma_f32 v[8:9], v[8:9], v[136:137], v[72:73]
	v_pk_fma_f32 v[6:7], v[6:7], v[134:135], v[70:71]
	v_pk_fma_f32 v[4:5], v[4:5], v[132:133], v[68:69]
	v_pk_fma_f32 v[2:3], v[2:3], v[130:131], v[66:67]
	global_store_dwordx4 v[96:97], v[62:65], off
	global_store_dwordx4 v[96:97], v[58:61], off offset:64
	global_store_dwordx4 v[96:97], v[54:57], off offset:512
	global_store_dwordx4 v[50:51], v[46:49], off
	global_store_dwordx4 v[50:51], v[42:45], off offset:64
	global_store_dwordx4 v[50:51], v[38:41], off offset:512
	global_store_dwordx4 v[34:35], v[30:33], off
	global_store_dwordx4 v[34:35], v[26:29], off offset:64
	global_store_dwordx4 v[34:35], v[22:25], off offset:512
	global_store_dwordx4 v[18:19], v[14:17], off
	global_store_dwordx4 v[18:19], v[10:13], off offset:64
	global_store_dwordx4 v[18:19], v[6:9], off offset:512
	global_store_dwordx4 v[18:19], v[2:5], off offset:576
	s_waitcnt vmcnt(0)
	s_cbranch_scc0 .LBB0_206
	s_barrier
	s_branch .LBB0_206

; DI void norm_row(const Params& p, int layer, int which, int t, int lane) {
;   const float* g = (which ? p.norm_ffn : p.norm_attn) + layer * DM;
;   const float* xr = which ? (const float*)xrow_dst(p, t) : xrow_src(p, layer, t);
;   const float* md = p.mod + ((size_t)layer * 5 + mb_of(t)) * 6144 + (which ? 3 * 1024 : 0);
;   float4 v[4];
;   float ss = 0.f;
; #pragma unroll
;   for (int j = 0; j < 4; ++j) {
;     v[j] = *(const float4*)(xr + lane * 4 + 256 * j);
;     ss += v[j].x * v[j].x + v[j].y * v[j].y + v[j].z * v[j].z + v[j].w * v[j].w;
;   }
; #pragma unroll
;   for (int o = 32; o >= 1; o >>= 1) ss += __shfl_xor(ss, o);
;   float r = rsqrtf(ss * (1.f / 1024.f) + EPSV);
; #pragma unroll
;   for (int j = 0; j < 4; ++j) {
;     int col = lane * 4 + 256 * j;
;     float4 gg = *(const float4*)(g + col);
;     float4 sh = *(const float4*)(md + col);
;     float4 sc = *(const float4*)(md + 1024 + col);
; DI void norm_static(const Params& p, int layer, int which, int row0, int row1) {
;     ...
;   for (int t = row0 + blockIdx.x * 8 + wid; t < row1; t += gridDim.x * 8) norm_row(p, layer, which, t, lane);
.LBB0_223:
	v_add_u32_e32 v2, 0x4000, v54
	v_mov_b64_e32 v[4:5], s[76:77]
	v_mov_b64_e32 v[6:7], s[64:65]
	v_cmp_gt_i32_e32 vcc, s10, v2
	v_ashrrev_i32_e32 v3, 31, v2
	v_lshlrev_b64 v[22:23], 11, v[2:3]
	v_cndmask_b32_e32 v9, 0, v3, vcc
	v_cndmask_b32_e32 v8, v54, v2, vcc
	v_cndmask_b32_e32 v5, v7, v5, vcc
	v_cndmask_b32_e32 v4, v6, v4, vcc
	v_lshlrev_b64 v[6:7], 12, v[8:9]
	v_lshl_add_u64 v[4:5], v[4:5], 0, v[6:7]
	v_lshl_add_u64 v[18:19], v[4:5], 0, v[0:1]
	v_and_b32_e32 v4, 64, v211
	v_add_u32_e32 v4, 64, v4
	v_xor_b32_e32 v5, 32, v211
	v_cmp_lt_i32_e32 vcc, v5, v4
	v_min_i32_e32 v6, 0x4000, v2
	v_ashrrev_i32_e32 v6, 12, v6
	v_cndmask_b32_e32 v5, v211, v5, vcc
	v_lshlrev_b32_e32 v55, 2, v5
	v_xor_b32_e32 v5, 16, v211
	v_cmp_lt_i32_e32 vcc, v5, v4
	v_add_u32_e32 v6, s8, v6
	v_mul_hi_i32_i24_e32 v7, 0x6000, v6
	v_cndmask_b32_e32 v5, v211, v5, vcc
	v_lshlrev_b32_e32 v56, 2, v5
	v_xor_b32_e32 v5, 8, v211
	v_cmp_lt_i32_e32 vcc, v5, v4
	v_mul_i32_i24_e32 v6, 0x6000, v6
	v_lshl_add_u64 v[6:7], s[62:63], 0, v[6:7]
	v_cndmask_b32_e32 v5, v211, v5, vcc
	v_lshlrev_b32_e32 v57, 2, v5
	v_xor_b32_e32 v5, 4, v211
	v_cmp_lt_i32_e32 vcc, v5, v4
	v_lshl_add_u64 v[20:21], v[6:7], 0, s[18:19]
	v_lshl_add_u64 v[46:47], v[6:7], 0, s[96:97]
	v_cndmask_b32_e32 v5, v211, v5, vcc
	s_waitcnt vmcnt(0)
	v_lshlrev_b32_e32 v68, 2, v5
	v_xor_b32_e32 v5, 2, v211
	v_cmp_lt_i32_e32 vcc, v5, v4
	v_lshl_add_u64 v[2:3], v[20:21], 0, v[0:1]
	v_lshl_add_u64 v[14:15], v[46:47], 0, v[0:1]
	v_cndmask_b32_e32 v5, v211, v5, vcc
	v_lshlrev_b32_e32 v69, 2, v5
	v_xor_b32_e32 v5, 1, v211
	v_cmp_lt_i32_e32 vcc, v5, v4
	v_lshl_add_u64 v[36:37], v[28:29], 0, v[22:23]
	v_mov_b32_e32 v31, v1
	v_cndmask_b32_e32 v4, v211, v5, vcc
	v_lshlrev_b32_e32 v70, 2, v4
	s_waitcnt vmcnt(0)
	global_load_dwordx4 v[10:13], v[18:19], off
	global_load_dwordx4 v[6:9], v[26:27], off
	s_nop 0
	global_load_dwordx4 v[2:5], v[2:3], off
	s_nop 0
	global_load_dwordx4 v[14:17], v[14:15], off
	v_mov_b32_e32 v33, v1
	v_mov_b32_e32 v35, v1
	v_lshl_add_u64 v[44:45], v[20:21], 0, v[30:31]
	v_lshl_add_u64 v[52:53], v[20:21], 0, v[34:35]
	v_lshl_add_u64 v[42:43], v[46:47], 0, v[30:31]
	v_add_u32_e32 v54, s9, v54
	s_waitcnt vmcnt(0) lgkmcnt(0)
	v_mov_b32_e32 v50, v11
	v_mov_b32_e32 v48, v10
	v_mov_b32_e32 v22, v12
	v_pk_add_f32 v[40:41], v[14:15], 1.0 op_sel_hi:[1,0]
	v_pk_add_f32 v[38:39], v[16:17], 1.0 op_sel_hi:[1,0]
	global_load_dwordx4 v[14:17], v[18:19], off offset:1024
	v_mov_b32_e32 v24, v13
	s_waitcnt vmcnt(0) lgkmcnt(0)
	v_mov_b32_e32 v51, v15
	v_mov_b32_e32 v49, v14
	v_pk_mul_f32 v[50:51], v[50:51], v[50:51]
	v_mov_b32_e32 v23, v16
	v_pk_fma_f32 v[48:49], v[48:49], v[48:49], v[50:51]
	v_mov_b32_e32 v25, v17
	v_pk_fma_f32 v[22:23], v[22:23], v[22:23], v[48:49]
	v_lshl_add_u64 v[50:51], v[20:21], 0, v[32:33]
	v_pk_fma_f32 v[58:59], v[24:25], v[24:25], v[22:23]
	global_load_dwordx4 v[22:25], v[18:19], off offset:2048
	v_add_f32_e32 v31, v58, v59
	global_load_dwordx4 v[18:21], v[18:19], off offset:3072
	v_lshl_add_u64 v[48:49], v[46:47], 0, v[32:33]
	v_lshl_add_u64 v[46:47], v[46:47], 0, v[34:35]
	s_waitcnt vmcnt(0) lgkmcnt(0)
	v_mov_b32_e32 v66, v23
	v_mov_b32_e32 v64, v22
	v_mov_b32_e32 v67, v19
	v_mov_b32_e32 v65, v18
	v_pk_mul_f32 v[66:67], v[66:67], v[66:67]
	v_mov_b32_e32 v60, v24
	v_mov_b32_e32 v61, v20
	v_pk_fma_f32 v[64:65], v[64:65], v[64:65], v[66:67]
	v_mov_b32_e32 v62, v25
	v_mov_b32_e32 v63, v21
	v_pk_fma_f32 v[60:61], v[60:61], v[60:61], v[64:65]
	s_nop 0
	v_pk_fma_f32 v[60:61], v[62:63], v[62:63], v[60:61]
	s_nop 0
	v_add_f32_e32 v31, v31, v60
	v_add_f32_e32 v31, v31, v61
	ds_bpermute_b32 v33, v55, v31
	s_waitcnt lgkmcnt(0)
; DI void norm_row(const Params& p, int layer, int which, int t, int lane) {
;     ...
;   for (int o = 32; o >= 1; o >>= 1) ss += __shfl_xor(ss, o);
;   float r = rsqrtf(ss * (1.f / 1024.f) + EPSV);
; #pragma unroll
;   for (int j = 0; j < 4; ++j) {
;     int col = lane * 4 + 256 * j;
;     float4 gg = *(const float4*)(g + col);
;     float4 sh = *(const float4*)(md + col);
;     float4 sc = *(const float4*)(md + 1024 + col);
;     float o0 = v[j].x * r * gg.x * (1.f + sc.x) + sh.x;
;     float o1 = v[j].y * r * gg.y * (1.f + sc.y) + sh.y;
;     float o2 = v[j].z * r * gg.z * (1.f + sc.z) + sh.z;
;     float o3 = v[j].w * r * gg.w * (1.f + sc.w) + sh.w;
;     *(uint2*)(p.H + (size_t)t * LDK + col) = make_uint2(pack_bf16(o0, o1), pack_bf16(o2, o3));
;   }
; DI void norm_static(const Params& p, int layer, int which, int row0, int row1) {
;     ...
;   for (int t = row0 + blockIdx.x * 8 + wid; t < row1; t += gridDim.x * 8) norm_row(p, layer, which, t, lane);
	v_add_f32_e32 v31, v31, v33
	ds_bpermute_b32 v33, v56, v31
	s_waitcnt lgkmcnt(0)
	v_add_f32_e32 v31, v31, v33
	ds_bpermute_b32 v33, v57, v31
	s_waitcnt lgkmcnt(0)
	v_add_f32_e32 v31, v31, v33
	ds_bpermute_b32 v33, v68, v31
	s_waitcnt lgkmcnt(0)
	v_add_f32_e32 v31, v31, v33
	ds_bpermute_b32 v33, v69, v31
	s_waitcnt lgkmcnt(0)
	v_add_f32_e32 v31, v31, v33
	ds_bpermute_b32 v33, v70, v31
	s_waitcnt lgkmcnt(0)
	v_add_f32_e32 v31, v31, v33
	v_fmamk_f32 v31, v31, 0x3a800000, v210
	v_cmp_gt_f32_e32 vcc, s11, v31
	v_mul_f32_e32 v33, 0x4b800000, v31
	s_nop 0
	v_cndmask_b32_e32 v31, v31, v33, vcc
	v_rsq_f32_e32 v31, v31
	s_nop 0
	v_mul_f32_e32 v33, 0x45800000, v31
	v_cndmask_b32_e32 v56, v31, v33, vcc
	v_pk_mul_f32 v[10:11], v[10:11], v[56:57] op_sel_hi:[1,0]
	v_pk_mul_f32 v[14:15], v[14:15], v[56:57] op_sel_hi:[1,0]
	v_pk_mul_f32 v[6:7], v[6:7], v[10:11]
	s_nop 0
	v_pk_fma_f32 v[2:3], v[40:41], v[6:7], v[2:3]
	v_pk_mul_f32 v[6:7], v[12:13], v[56:57] op_sel_hi:[1,0]
	v_cvt_pk_bf16_f32 v2, v2, v3
	v_pk_mul_f32 v[6:7], v[8:9], v[6:7]
	s_nop 0
	v_pk_fma_f32 v[4:5], v[6:7], v[38:39], v[4:5]
	s_nop 0
	v_cvt_pk_bf16_f32 v3, v4, v5
	global_store_dwordx2 v[36:37], v[2:3], off
	global_load_dwordx4 v[2:5], v[26:27], off offset:1024
	s_nop 0
	global_load_dwordx4 v[6:9], v[44:45], off
	global_load_dwordx4 v[10:13], v[42:43], off
	s_waitcnt vmcnt(2)
	v_pk_mul_f32 v[2:3], v[14:15], v[2:3]
	v_pk_mul_f32 v[14:15], v[22:23], v[56:57] op_sel_hi:[1,0]
	s_waitcnt vmcnt(0)
	v_pk_add_f32 v[10:11], v[10:11], 1.0 op_sel_hi:[1,0]
	s_nop 0
	v_pk_fma_f32 v[2:3], v[2:3], v[10:11], v[6:7]
	v_pk_mul_f32 v[6:7], v[16:17], v[56:57] op_sel_hi:[1,0]
	v_cvt_pk_bf16_f32 v2, v2, v3
	v_pk_mul_f32 v[4:5], v[6:7], v[4:5]
	v_pk_add_f32 v[6:7], v[12:13], 1.0 op_sel_hi:[1,0]
	s_nop 0
	v_pk_fma_f32 v[4:5], v[4:5], v[6:7], v[8:9]
	s_nop 0
	v_cvt_pk_bf16_f32 v3, v4, v5
	global_store_dwordx2 v[36:37], v[2:3], off offset:512
	global_load_dwordx4 v[2:5], v[26:27], off offset:2048
	s_nop 0
	global_load_dwordx4 v[6:9], v[50:51], off
	global_load_dwordx4 v[10:13], v[48:49], off
	s_waitcnt vmcnt(2)
	v_pk_mul_f32 v[2:3], v[14:15], v[2:3]
	v_pk_mul_f32 v[14:15], v[18:19], v[56:57] op_sel_hi:[1,0]
	s_waitcnt vmcnt(0)
	v_pk_add_f32 v[10:11], v[10:11], 1.0 op_sel_hi:[1,0]
	s_nop 0
	v_pk_fma_f32 v[2:3], v[2:3], v[10:11], v[6:7]
	v_pk_mul_f32 v[6:7], v[24:25], v[56:57] op_sel_hi:[1,0]
	v_cvt_pk_bf16_f32 v2, v2, v3
	v_pk_mul_f32 v[4:5], v[6:7], v[4:5]
	v_pk_add_f32 v[6:7], v[12:13], 1.0 op_sel_hi:[1,0]
	s_nop 0
	v_pk_fma_f32 v[4:5], v[4:5], v[6:7], v[8:9]
	s_nop 0
	v_cvt_pk_bf16_f32 v3, v4, v5
	global_store_dwordx2 v[36:37], v[2:3], off offset:1024
	global_load_dwordx4 v[2:5], v[26:27], off offset:3072
	s_nop 0
	global_load_dwordx4 v[6:9], v[52:53], off
	global_load_dwordx4 v[10:13], v[46:47], off
	s_waitcnt vmcnt(2)
	v_pk_mul_f32 v[2:3], v[14:15], v[2:3]
	s_waitcnt vmcnt(0)
	v_pk_add_f32 v[10:11], v[10:11], 1.0 op_sel_hi:[1,0]
	s_nop 0
	v_pk_fma_f32 v[2:3], v[2:3], v[10:11], v[6:7]
	v_pk_mul_f32 v[6:7], v[20:21], v[56:57] op_sel_hi:[1,0]
	v_cvt_pk_bf16_f32 v2, v2, v3
	v_pk_mul_f32 v[4:5], v[6:7], v[4:5]
	v_pk_add_f32 v[6:7], v[12:13], 1.0 op_sel_hi:[1,0]
	s_nop 0
	v_pk_fma_f32 v[4:5], v[4:5], v[6:7], v[8:9]
	s_nop 0
	v_cvt_pk_bf16_f32 v3, v4, v5
	global_store_dwordx2 v[36:37], v[2:3], off offset:1536
	v_add_u32_e32 v2, 0x4000, v54
	v_cmp_lt_i32_e32 vcc, s14, v2
	s_or_b64 s[2:3], vcc, s[2:3]
	s_andn2_b64 exec, exec, s[2:3]
	s_cbranch_execnz .LBB0_223

;   DI void operator()(const f32x4 (&acc)[2][2][4][2], const Unit& u, int wr, int wc, int fr, int fq) const {
;     asm volatile("" ::: "memory");
;     const int row0 = u.pm * BM + wr * 64 + fr, col0 = u.pn * BM + wc * 32 + 4 * fq;
;     f32x4 gv[2][2];
; #pragma unroll
;     for (int bj = 0; bj < 2; ++bj)
; #pragma unroll
;       for (int n = 0; n < 2; ++n) gv[bj][n] = *(const f32x4*)(gate + col0 + bj * HALF + n * 16);
; #pragma unroll
;     for (int ai = 0; ai < 2; ++ai) {
;       f32x4 sv[4][2][2];
; #pragma unroll
;       for (int m = 0; m < 4; ++m) {
;         const size_t ro = (size_t)(row0 + ai * HALF + m * 16) * DM + col0;
; #pragma unroll
;         for (int bj = 0; bj < 2; ++bj)
; #pragma unroll
;           for (int n = 0; n < 2; ++n) sv[m][bj][n] = *(const f32x4*)(src + ro + bj * HALF + n * 16);
;       }
; #pragma unroll
;       for (int m = 0; m < 4; ++m) {
;         const size_t ro = (size_t)(row0 + ai * HALF + m * 16) * DM + col0;
; #pragma unroll
;         for (int bj = 0; bj < 2; ++bj)
; #pragma unroll
;           for (int n = 0; n < 2; ++n) *(f32x4*)(dst + ro + bj * HALF + n * 16) = sv[m][bj][n] + gv[bj][n] * acc[ai][bj][m][n];
;       }
.LBB0_493:
	s_lshl_b32 s0, s15, 8
	v_lshl_or_b32 v0, v132, 2, s0
	v_or_b32_e32 v0, s16, v0
	v_readlane_b32 s0, v255, 10
	v_lshlrev_b64 v[174:175], 2, v[0:1]
	v_readlane_b32 s1, v255, 11
	v_lshl_add_u32 v146, s13, 8, v146
	v_ashrrev_i32_e32 v147, 31, v146
	v_lshl_add_u64 v[126:127], s[0:1], 0, v[174:175]
	v_readlane_b32 s0, v255, 6
	v_readlane_b32 s1, v255, 7
	v_lshlrev_b64 v[186:187], 12, v[146:147]
	global_load_dwordx4 v[142:145], v[126:127], off
	global_load_dwordx4 v[138:141], v[126:127], off offset:64
	global_load_dwordx4 v[130:133], v[126:127], off offset:512
	s_nop 0
	global_load_dwordx4 v[126:129], v[126:127], off offset:576
	v_lshl_add_u64 v[176:177], s[0:1], 0, v[174:175]
	s_waitcnt vmcnt(0)
	v_lshl_add_u64 v[148:149], v[176:177], 0, v[186:187]
	global_load_dwordx4 v[190:193], v[148:149], off
	global_load_dwordx4 v[198:201], v[148:149], off offset:64
	global_load_dwordx4 v[202:205], v[148:149], off offset:512
	global_load_dwordx4 v[206:209], v[148:149], off offset:576
	v_or_b32_e32 v148, 16, v146
	v_ashrrev_i32_e32 v149, 31, v148
	v_lshlrev_b64 v[180:181], 12, v[148:149]
	v_lshl_add_u64 v[148:149], v[176:177], 0, v[180:181]
	global_load_dwordx4 v[214:217], v[148:149], off
	global_load_dwordx4 v[218:221], v[148:149], off offset:64
	global_load_dwordx4 v[222:225], v[148:149], off offset:512
	global_load_dwordx4 v[226:229], v[148:149], off offset:576
	v_or_b32_e32 v148, 32, v146
	v_ashrrev_i32_e32 v149, 31, v148
	v_lshlrev_b64 v[182:183], 12, v[148:149]
	v_or_b32_e32 v146, 48, v146
	v_lshl_add_u64 v[148:149], v[176:177], 0, v[182:183]
	v_ashrrev_i32_e32 v147, 31, v146
	global_load_dwordx4 v[230:233], v[148:149], off
	global_load_dwordx4 v[166:169], v[148:149], off offset:64
	global_load_dwordx4 v[162:165], v[148:149], off offset:512
	global_load_dwordx4 v[158:161], v[148:149], off offset:576
	v_lshlrev_b64 v[188:189], 12, v[146:147]
	v_lshl_add_u64 v[146:147], v[176:177], 0, v[188:189]
	global_load_dwordx4 v[170:173], v[146:147], off
	global_load_dwordx4 v[154:157], v[146:147], off offset:64
	global_load_dwordx4 v[150:153], v[146:147], off offset:512
	s_nop 0
	global_load_dwordx4 v[146:149], v[146:147], off offset:576
	v_readlane_b32 s2, v254, 31
	v_readlane_b32 s3, v254, 32
	s_mov_b64 s[0:1], 0x80000
	s_cmpk_lt_u32 s12, 0x100
	v_lshl_add_u64 v[184:185], s[2:3], 0, v[186:187]
	v_lshl_add_u64 v[184:185], v[184:185], 0, v[174:175]
	s_waitcnt vmcnt(0) lgkmcnt(0)
	v_pk_fma_f32 v[136:137], v[136:137], v[144:145], v[192:193]
	v_pk_fma_f32 v[124:125], v[124:125], v[140:141], v[200:201]
	v_pk_fma_f32 v[122:123], v[122:123], v[138:139], v[198:199]
	v_pk_fma_f32 v[116:117], v[116:117], v[128:129], v[208:209]
	v_pk_fma_f32 v[114:115], v[114:115], v[126:127], v[206:207]
	global_store_dwordx4 v[184:185], v[114:117], off offset:576
	v_pk_fma_f32 v[134:135], v[134:135], v[142:143], v[190:191]
	global_store_dwordx4 v[184:185], v[122:125], off offset:64
	v_lshl_add_u64 v[114:115], s[2:3], 0, v[180:181]
	v_lshl_add_u64 v[114:115], v[114:115], 0, v[174:175]
	v_pk_fma_f32 v[100:101], v[100:101], v[128:129], v[228:229]
	v_pk_fma_f32 v[98:99], v[98:99], v[126:127], v[226:227]
	global_store_dwordx4 v[114:115], v[98:101], off offset:576
	v_pk_fma_f32 v[120:121], v[120:121], v[132:133], v[204:205]
	v_pk_fma_f32 v[118:119], v[118:119], v[130:131], v[202:203]
	v_lshl_add_u64 v[98:99], s[2:3], 0, v[182:183]
	v_lshl_add_u64 v[98:99], v[98:99], 0, v[174:175]
	v_pk_fma_f32 v[84:85], v[84:85], v[128:129], v[160:161]
	v_pk_fma_f32 v[82:83], v[82:83], v[126:127], v[158:159]
	global_store_dwordx4 v[98:99], v[82:85], off offset:576
	v_pk_fma_f32 v[112:113], v[112:113], v[144:145], v[216:217]
	v_pk_fma_f32 v[110:111], v[110:111], v[142:143], v[214:215]
	v_lshl_add_u64 v[82:83], s[2:3], 0, v[188:189]
	v_pk_fma_f32 v[108:109], v[108:109], v[140:141], v[220:221]
	v_pk_fma_f32 v[106:107], v[106:107], v[138:139], v[218:219]
	v_pk_fma_f32 v[104:105], v[104:105], v[132:133], v[224:225]
	v_pk_fma_f32 v[102:103], v[102:103], v[130:131], v[222:223]
	v_pk_fma_f32 v[96:97], v[96:97], v[144:145], v[232:233]
	v_pk_fma_f32 v[94:95], v[94:95], v[142:143], v[230:231]
	v_pk_fma_f32 v[92:93], v[92:93], v[140:141], v[168:169]
	v_pk_fma_f32 v[90:91], v[90:91], v[138:139], v[166:167]
	v_pk_fma_f32 v[88:89], v[88:89], v[132:133], v[164:165]
	v_pk_fma_f32 v[86:87], v[86:87], v[130:131], v[162:163]
	v_pk_fma_f32 v[80:81], v[80:81], v[144:145], v[172:173]
	v_pk_fma_f32 v[78:79], v[78:79], v[142:143], v[170:171]
	v_lshl_add_u64 v[82:83], v[82:83], 0, v[174:175]
	v_pk_fma_f32 v[76:77], v[76:77], v[140:141], v[156:157]
	v_pk_fma_f32 v[74:75], v[74:75], v[138:139], v[154:155]
	v_pk_fma_f32 v[72:73], v[72:73], v[132:133], v[152:153]
	v_pk_fma_f32 v[70:71], v[70:71], v[130:131], v[150:151]
	v_pk_fma_f32 v[68:69], v[68:69], v[128:129], v[148:149]
	v_pk_fma_f32 v[66:67], v[66:67], v[126:127], v[146:147]
	v_lshl_add_u64 v[124:125], v[186:187], 0, s[0:1]
	global_store_dwordx4 v[184:185], v[134:137], off
	global_store_dwordx4 v[184:185], v[118:121], off offset:512
	global_store_dwordx4 v[114:115], v[110:113], off
	global_store_dwordx4 v[114:115], v[106:109], off offset:64
	global_store_dwordx4 v[114:115], v[102:105], off offset:512
	global_store_dwordx4 v[98:99], v[94:97], off
	global_store_dwordx4 v[98:99], v[90:93], off offset:64
	global_store_dwordx4 v[98:99], v[86:89], off offset:512
	global_store_dwordx4 v[82:83], v[78:81], off
	global_store_dwordx4 v[82:83], v[74:77], off offset:64
	global_store_dwordx4 v[82:83], v[70:73], off offset:512
	global_store_dwordx4 v[82:83], v[66:69], off offset:576
	s_mov_b64 s[0:1], 0x90000
	v_lshl_add_u64 v[150:151], v[186:187], 0, s[0:1]
	v_lshl_add_u64 v[66:67], v[176:177], 0, v[124:125]
	global_load_dwordx4 v[80:83], v[66:67], off
	global_load_dwordx4 v[84:87], v[66:67], off offset:64
	global_load_dwordx4 v[88:91], v[66:67], off offset:512
	global_load_dwordx4 v[92:95], v[66:67], off offset:576
	v_lshl_add_u64 v[66:67], v[176:177], 0, v[150:151]
	s_mov_b64 s[0:1], 0xa0000
	global_load_dwordx4 v[96:99], v[66:67], off
	global_load_dwordx4 v[100:103], v[66:67], off offset:64
	global_load_dwordx4 v[104:107], v[66:67], off offset:512
	global_load_dwordx4 v[108:111], v[66:67], off offset:576
	v_lshl_add_u64 v[152:153], v[186:187], 0, s[0:1]
	v_lshl_add_u64 v[66:67], v[176:177], 0, v[152:153]
	s_mov_b64 s[0:1], 0xb0000
	global_load_dwordx4 v[112:115], v[66:67], off
	global_load_dwordx4 v[116:119], v[66:67], off offset:64
	global_load_dwordx4 v[120:123], v[66:67], off offset:512
	global_load_dwordx4 v[134:137], v[66:67], off offset:576
	v_lshl_add_u64 v[78:79], v[186:187], 0, s[0:1]
	v_lshl_add_u64 v[66:67], v[176:177], 0, v[78:79]
	global_load_dwordx4 v[146:149], v[66:67], off
	global_load_dwordx4 v[74:77], v[66:67], off offset:64
	global_load_dwordx4 v[70:73], v[66:67], off offset:512
	s_nop 0
	global_load_dwordx4 v[66:69], v[66:67], off offset:576
	s_waitcnt vmcnt(0) lgkmcnt(0)
; #define PG8_WAIT_V(n) asm volatile("s_waitcnt vmcnt(" #n ")" ::: "memory")
; #define PG8_BAR __builtin_amdgcn_s_barrier()
; template <class Epi, class Sched>
; DI void gemm_phase(LAS unsigned char* lds, const Gemm g, const Sched& S, const Epi& E) {
;     ...
;   PG8_WAIT_V(0);
;   if (wr == 0) PG8_BAR;
;   DI void operator()(const f32x4 (&acc)[2][2][4][2], const Unit& u, int wr, int wc, int fr, int fq) const {
;     ...
; #pragma unroll
;       for (int m = 0; m < 4; ++m) {
;         const size_t ro = (size_t)(row0 + ai * HALF + m * 16) * DM + col0;
; #pragma unroll
;         for (int bj = 0; bj < 2; ++bj)
; #pragma unroll
;           for (int n = 0; n < 2; ++n) *(f32x4*)(dst + ro + bj * HALF + n * 16) = sv[m][bj][n] + gv[bj][n] * acc[ai][bj][m][n];
;       }
	v_pk_fma_f32 v[62:63], v[62:63], v[142:143], v[80:81]
	v_lshl_add_u64 v[80:81], s[2:3], 0, v[124:125]
	v_lshl_add_u64 v[80:81], v[80:81], 0, v[174:175]
	v_pk_fma_f32 v[48:49], v[48:49], v[128:129], v[94:95]
	v_pk_fma_f32 v[46:47], v[46:47], v[126:127], v[92:93]
	global_store_dwordx4 v[80:81], v[46:49], off offset:576
	v_pk_fma_f32 v[32:33], v[32:33], v[128:129], v[110:111]
	v_pk_fma_f32 v[30:31], v[30:31], v[126:127], v[108:109]
	v_pk_fma_f32 v[46:47], v[50:51], v[142:143], v[96:97]
	v_lshl_add_u64 v[50:51], s[2:3], 0, v[150:151]
	v_lshl_add_u64 v[50:51], v[50:51], 0, v[174:175]
	global_store_dwordx4 v[50:51], v[30:33], off offset:576
	v_pk_fma_f32 v[16:17], v[16:17], v[128:129], v[136:137]
	v_pk_fma_f32 v[14:15], v[14:15], v[126:127], v[134:135]
	v_pk_fma_f32 v[30:31], v[34:35], v[142:143], v[112:113]
	v_lshl_add_u64 v[34:35], s[2:3], 0, v[152:153]
	v_lshl_add_u64 v[34:35], v[34:35], 0, v[174:175]
	global_store_dwordx4 v[34:35], v[14:17], off offset:576
	v_pk_fma_f32 v[64:65], v[64:65], v[144:145], v[82:83]
	v_pk_fma_f32 v[60:61], v[60:61], v[140:141], v[86:87]
	v_pk_fma_f32 v[14:15], v[18:19], v[142:143], v[146:147]
	v_lshl_add_u64 v[18:19], s[2:3], 0, v[78:79]
	v_pk_fma_f32 v[58:59], v[58:59], v[138:139], v[84:85]
	v_pk_fma_f32 v[56:57], v[56:57], v[132:133], v[90:91]
	v_pk_fma_f32 v[54:55], v[54:55], v[130:131], v[88:89]
	v_pk_fma_f32 v[48:49], v[52:53], v[144:145], v[98:99]
	v_pk_fma_f32 v[44:45], v[44:45], v[140:141], v[102:103]
	v_pk_fma_f32 v[42:43], v[42:43], v[138:139], v[100:101]
	v_pk_fma_f32 v[40:41], v[40:41], v[132:133], v[106:107]
	v_pk_fma_f32 v[38:39], v[38:39], v[130:131], v[104:105]
	v_pk_fma_f32 v[32:33], v[36:37], v[144:145], v[114:115]
	v_pk_fma_f32 v[28:29], v[28:29], v[140:141], v[118:119]
	v_pk_fma_f32 v[26:27], v[26:27], v[138:139], v[116:117]
	v_pk_fma_f32 v[24:25], v[24:25], v[132:133], v[122:123]
	v_pk_fma_f32 v[22:23], v[22:23], v[130:131], v[120:121]
	v_pk_fma_f32 v[16:17], v[20:21], v[144:145], v[148:149]
	v_lshl_add_u64 v[18:19], v[18:19], 0, v[174:175]
	v_pk_fma_f32 v[12:13], v[12:13], v[140:141], v[76:77]
	v_pk_fma_f32 v[10:11], v[10:11], v[138:139], v[74:75]
	v_pk_fma_f32 v[8:9], v[8:9], v[132:133], v[72:73]
	v_pk_fma_f32 v[6:7], v[6:7], v[130:131], v[70:71]
	v_pk_fma_f32 v[4:5], v[4:5], v[128:129], v[68:69]
	v_pk_fma_f32 v[2:3], v[2:3], v[126:127], v[66:67]
	global_store_dwordx4 v[80:81], v[62:65], off
	global_store_dwordx4 v[80:81], v[58:61], off offset:64
	global_store_dwordx4 v[80:81], v[54:57], off offset:512
	global_store_dwordx4 v[50:51], v[46:49], off
	global_store_dwordx4 v[50:51], v[42:45], off offset:64
	global_store_dwordx4 v[50:51], v[38:41], off offset:512
	global_store_dwordx4 v[34:35], v[30:33], off
	global_store_dwordx4 v[34:35], v[26:29], off offset:64
	global_store_dwordx4 v[34:35], v[22:25], off offset:512
	global_store_dwordx4 v[18:19], v[14:17], off
	global_store_dwordx4 v[18:19], v[10:13], off offset:64
	global_store_dwordx4 v[18:19], v[6:9], off offset:512
	global_store_dwordx4 v[18:19], v[2:5], off offset:576
	s_waitcnt vmcnt(0)
	s_cbranch_scc0 .LBB0_495
	s_barrier

; template <int R>
; DI void norm_rows(const Params& p, int layer, int which, int t0, int tstep, int lane) {
;   const float* g = (which ? p.norm_ffn : p.norm_attn) + layer * DM;
;   const float* md = p.mod + ((size_t)layer * 5 + mb_of(t0)) * 6144 + (which ? 3 * 1024 : 0);
;   float4 v[R][4];
;   float ss[R];
; #pragma unroll
;   for (int r = 0; r < R; ++r) {
;     const float* xr = which ? (const float*)xrow_dst(p, t0 + r * tstep) : xrow_src(p, layer, t0 + r * tstep);
; #pragma unroll
;     for (int j = 0; j < 4; ++j) v[r][j] = *(const float4*)(xr + lane * 4 + 256 * j);
;   }
; #pragma unroll
;   for (int r = 0; r < R; ++r) {
;     ss[r] = 0.f;
; #pragma unroll
;     for (int j = 0; j < 4; ++j) ss[r] += v[r][j].x * v[r][j].x + v[r][j].y * v[r][j].y + v[r][j].z * v[r][j].z + v[r][j].w * v[r][j].w;
;   }
; #pragma unroll
;   for (int o = 32; o >= 1; o >>= 1)
; #pragma unroll
;     for (int r = 0; r < R; ++r) ss[r] += __shfl_xor(ss[r], o);
; #pragma unroll
;   for (int r = 0; r < R; ++r) ss[r] = rsqrtf(ss[r] * (1.f / 1024.f) + EPSV);
;   float4 mm[4], sh[4];
; #pragma unroll
;   for (int j = 0; j < 4; ++j) {
;     int col = lane * 4 + 256 * j;
;     float4 gg = *(const float4*)(g + col);
;     float4 sc = *(const float4*)(md + 1024 + col);
;     sh[j] = *(const float4*)(md + col);
;     mm[j] = make_float4(gg.x * (1.f + sc.x), gg.y * (1.f + sc.y), gg.z * (1.f + sc.z), gg.w * (1.f + sc.w));
;   }
; DI void norm_dyn(const Params& p, int layer, int which, int row0, int row1, unsigned* ctr) {
;     ...
;   while (true) {
;     int ch = grab(ctr);
;     if (ch >= nchunk) break;
;     norm_rows<4>(p, layer, which, row0 + ch * 32 + wid, 8, lane);
.LBB0_882:
	s_or_b64 exec, exec, s[0:1]
	s_waitcnt lgkmcnt(0)
	s_barrier
	ds_read_b32 v2, v1
	s_movk_i32 s0, 0x1ff
	s_waitcnt lgkmcnt(0)
	s_barrier
	v_cmp_lt_i32_e32 vcc, s0, v2
	s_mov_b64 s[0:1], -1
	s_cbranch_vccnz .LBB0_877
	v_lshl_add_u32 v58, v2, 5, v104
	v_mov_b64_e32 v[2:3], s[12:13]
	v_mov_b64_e32 v[4:5], s[16:17]
	v_mov_b64_e32 v[6:7], s[76:77]
	v_mov_b64_e32 v[8:9], s[64:65]
	v_ashrrev_i32_e32 v59, 31, v58
	v_cndmask_b32_e64 v4, v8, v4, s[72:73]
	v_add_u32_e32 v8, 0xffffc000, v58
	v_cmp_gt_i32_e32 vcc, s28, v58
	v_cndmask_b32_e64 v5, v9, v5, s[72:73]
	v_cndmask_b32_e64 v6, v6, v2, s[72:73]
	v_cndmask_b32_e64 v7, v7, v3, s[72:73]
	v_cndmask_b32_e32 v3, 0, v59, vcc
	v_cndmask_b32_e32 v2, v8, v58, vcc
	v_cndmask_b32_e32 v5, v5, v7, vcc
	v_cndmask_b32_e32 v4, v4, v6, vcc
	v_lshlrev_b64 v[2:3], 12, v[2:3]
	v_add_u32_e32 v60, 8, v58
	s_movk_i32 s0, 0x3ff8
	v_lshl_add_u64 v[2:3], v[4:5], 0, v[2:3]
	v_add_u32_e32 v4, 0xffffc008, v58
	v_ashrrev_i32_e32 v61, 31, v60
	v_cmp_gt_i32_e32 vcc, s0, v58
	v_lshl_add_u64 v[2:3], v[2:3], 0, v[0:1]
	v_mov_b64_e32 v[12:13], s[12:13]
	v_cndmask_b32_e32 v5, 0, v61, vcc
	v_cndmask_b32_e32 v4, v4, v60, vcc
	v_mov_b64_e32 v[22:23], s[16:17]
	v_mov_b64_e32 v[24:25], s[76:77]
	v_mov_b64_e32 v[26:27], s[64:65]
	global_load_dwordx4 v[18:21], v[2:3], off
	global_load_dwordx4 v[14:17], v[2:3], off offset:1024
	v_lshlrev_b64 v[10:11], 12, v[4:5]
	global_load_dwordx4 v[6:9], v[2:3], off offset:2048
	s_nop 0
	global_load_dwordx4 v[2:5], v[2:3], off offset:3072
	v_add_u32_e32 v62, 16, v58
	v_cndmask_b32_e64 v22, v26, v22, s[72:73]
	v_cndmask_b32_e64 v23, v27, v23, s[72:73]
	v_cndmask_b32_e64 v12, v24, v12, s[72:73]
	v_cndmask_b32_e64 v13, v25, v13, s[72:73]
	v_cndmask_b32_e32 v13, v23, v13, vcc
	v_cndmask_b32_e32 v12, v22, v12, vcc
	v_lshl_add_u64 v[10:11], v[12:13], 0, v[10:11]
	v_lshl_add_u64 v[10:11], v[10:11], 0, v[0:1]
	s_movk_i32 s0, 0x3ff0
	v_add_u32_e32 v28, 0xffffc010, v58
	v_ashrrev_i32_e32 v63, 31, v62
	global_load_dwordx4 v[46:49], v[10:11], off
	global_load_dwordx4 v[30:33], v[10:11], off offset:1024
	v_cmp_gt_i32_e32 vcc, s0, v58
	v_mov_b64_e32 v[24:25], s[12:13]
	v_mov_b64_e32 v[26:27], s[16:17]
	v_cndmask_b32_e32 v13, 0, v63, vcc
	v_cndmask_b32_e32 v12, v28, v62, vcc
	v_lshlrev_b64 v[22:23], 12, v[12:13]
	global_load_dwordx4 v[34:37], v[10:11], off offset:2048
	s_nop 0
	global_load_dwordx4 v[10:13], v[10:11], off offset:3072
	v_mov_b64_e32 v[28:29], s[76:77]
	v_mov_b64_e32 v[38:39], s[64:65]
	v_add_u32_e32 v64, 24, v58
	v_cndmask_b32_e64 v26, v38, v26, s[72:73]
	v_cndmask_b32_e64 v27, v39, v27, s[72:73]
	v_cndmask_b32_e64 v24, v28, v24, s[72:73]
	v_cndmask_b32_e64 v25, v29, v25, s[72:73]
	s_movk_i32 s0, 0x3fe8
	v_add_u32_e32 v40, 0xffffc018, v58
	v_ashrrev_i32_e32 v65, 31, v64
	v_cndmask_b32_e32 v25, v27, v25, vcc
	v_cndmask_b32_e32 v24, v26, v24, vcc
	v_cmp_gt_i32_e32 vcc, s0, v58
	v_lshl_add_u64 v[22:23], v[24:25], 0, v[22:23]
	v_lshl_add_u64 v[38:39], v[22:23], 0, v[0:1]
	v_cndmask_b32_e32 v41, 0, v65, vcc
	v_cndmask_b32_e32 v40, v40, v64, vcc
	v_lshlrev_b64 v[66:67], 12, v[40:41]
	v_min_i32_e32 v40, 0x4000, v58
	v_ashrrev_i32_e32 v40, 12, v40
	v_ashrrev_i32_e32 v41, 31, v40
	global_load_dwordx4 v[26:29], v[38:39], off
	global_load_dwordx4 v[22:25], v[38:39], off offset:1024
	v_lshl_add_u64 v[68:69], s[4:5], 0, v[40:41]
	v_mov_b64_e32 v[40:41], s[62:63]
	s_movk_i32 s6, 0x6000
	v_mad_u64_u32 v[70:71], s[0:1], v68, s6, v[40:41]
	global_load_dwordx4 v[42:45], v[38:39], off offset:2048
	s_nop 0
	global_load_dwordx4 v[38:41], v[38:39], off offset:3072
	v_mad_i32_i24 v71, v69, s6, v71
	s_mov_b64 s[0:1], 0x1000
	v_lshl_add_u64 v[68:69], v[70:71], 0, s[0:1]
	v_mov_b64_e32 v[50:51], s[12:13]
	v_mov_b64_e32 v[52:53], s[76:77]
	v_mov_b64_e32 v[54:55], s[16:17]
	v_mov_b64_e32 v[56:57], s[64:65]
	v_lshl_add_u64 v[72:73], v[68:69], 0, v[0:1]
	v_lshlrev_b64 v[58:59], 11, v[58:59]
	global_load_dwordx4 v[106:109], v[72:73], off
	v_lshl_add_u64 v[90:91], v[76:77], 0, v[58:59]
	v_lshlrev_b64 v[58:59], 11, v[60:61]
	global_load_dwordx4 v[110:113], v[74:75], off
	v_lshl_add_u64 v[88:89], v[76:77], 0, v[58:59]
	v_lshlrev_b64 v[58:59], 11, v[62:63]
	v_lshl_add_u64 v[86:87], v[76:77], 0, v[58:59]
	v_lshlrev_b64 v[58:59], 11, v[64:65]
	v_lshl_add_u64 v[84:85], v[76:77], 0, v[58:59]
	v_cndmask_b32_e64 v54, v56, v54, s[72:73]
	v_cndmask_b32_e64 v55, v57, v55, s[72:73]
	v_cndmask_b32_e64 v50, v52, v50, s[72:73]
	v_cndmask_b32_e64 v51, v53, v51, s[72:73]
	v_cndmask_b32_e32 v51, v55, v51, vcc
	v_cndmask_b32_e32 v50, v54, v50, vcc
	v_lshl_add_u64 v[50:51], v[50:51], 0, v[66:67]
	s_waitcnt vmcnt(0) lgkmcnt(0)
; template <int R>
; DI void norm_rows(const Params& p, int layer, int which, int t0, int tstep, int lane) {
;     ...
; #pragma unroll
;   for (int r = 0; r < R; ++r) {
;     ss[r] = 0.f;
; #pragma unroll
;     for (int j = 0; j < 4; ++j) ss[r] += v[r][j].x * v[r][j].x + v[r][j].y * v[r][j].y + v[r][j].z * v[r][j].z + v[r][j].w * v[r][j].w;
;   }
; #pragma unroll
;   for (int o = 32; o >= 1; o >>= 1)
; #pragma unroll
;     for (int r = 0; r < R; ++r) ss[r] += __shfl_xor(ss[r], o);
; #pragma unroll
;   for (int r = 0; r < R; ++r) ss[r] = rsqrtf(ss[r] * (1.f / 1024.f) + EPSV);
;   float4 mm[4], sh[4];
; #pragma unroll
;   for (int j = 0; j < 4; ++j) {
;     int col = lane * 4 + 256 * j;
;     float4 gg = *(const float4*)(g + col);
;     float4 sc = *(const float4*)(md + 1024 + col);
;     sh[j] = *(const float4*)(md + col);
;     mm[j] = make_float4(gg.x * (1.f + sc.x), gg.y * (1.f + sc.y), gg.z * (1.f + sc.z), gg.w * (1.f + sc.w));
;   }
	v_mov_b32_e32 v64, v19
	v_mov_b32_e32 v65, v15
	v_mov_b32_e32 v62, v18
	v_mov_b32_e32 v63, v14
	v_pk_mul_f32 v[64:65], v[64:65], v[64:65]
	v_mov_b32_e32 v58, v20
	v_mov_b32_e32 v59, v16
	v_pk_fma_f32 v[62:63], v[62:63], v[62:63], v[64:65]
	v_mov_b32_e32 v94, v7
	v_mov_b32_e32 v95, v3
	v_mov_b32_e32 v60, v21
	v_mov_b32_e32 v61, v17
	v_pk_fma_f32 v[58:59], v[58:59], v[58:59], v[62:63]
	v_mov_b32_e32 v64, v6
	v_mov_b32_e32 v65, v2
	v_pk_mul_f32 v[94:95], v[94:95], v[94:95]
	v_pk_fma_f32 v[58:59], v[60:61], v[60:61], v[58:59]
	v_mov_b32_e32 v60, v8
	v_mov_b32_e32 v61, v4
	v_pk_fma_f32 v[64:65], v[64:65], v[64:65], v[94:95]
	v_mov_b32_e32 v96, v47
	v_mov_b32_e32 v97, v31
	v_mov_b32_e32 v62, v9
	v_mov_b32_e32 v63, v5
	v_pk_fma_f32 v[60:61], v[60:61], v[60:61], v[64:65]
	v_mov_b32_e32 v94, v46
	v_mov_b32_e32 v95, v30
	v_pk_mul_f32 v[96:97], v[96:97], v[96:97]
	v_mov_b32_e32 v79, v1
	v_pk_fma_f32 v[60:61], v[62:63], v[62:63], v[60:61]
	v_mov_b32_e32 v62, v48
	v_mov_b32_e32 v63, v32
	v_pk_fma_f32 v[94:95], v[94:95], v[94:95], v[96:97]
	v_mov_b32_e32 v98, v35
	v_mov_b32_e32 v99, v11
	v_lshl_add_u64 v[66:67], v[50:51], 0, v[0:1]
	v_and_b32_e32 v50, 64, v211
	v_lshl_add_u64 v[92:93], v[70:71], 0, v[0:1]
	v_lshl_add_u64 v[70:71], v[68:69], 0, v[78:79]
	v_mov_b32_e32 v64, v49
	v_mov_b32_e32 v65, v33
	v_pk_fma_f32 v[62:63], v[62:63], v[62:63], v[94:95]
	v_mov_b32_e32 v96, v34
	v_mov_b32_e32 v97, v10
	v_pk_mul_f32 v[98:99], v[98:99], v[98:99]
	v_add_u32_e32 v79, 64, v50
	v_xor_b32_e32 v50, 32, v211
	v_pk_fma_f32 v[62:63], v[64:65], v[64:65], v[62:63]
	v_mov_b32_e32 v64, v36
	v_mov_b32_e32 v65, v12
	v_pk_fma_f32 v[96:97], v[96:97], v[96:97], v[98:99]
	v_cmp_lt_i32_e32 vcc, v50, v79
	v_mov_b32_e32 v81, v1
	v_mov_b32_e32 v94, v37
	v_mov_b32_e32 v95, v13
	v_pk_fma_f32 v[64:65], v[64:65], v[64:65], v[96:97]
	v_cndmask_b32_e32 v50, v211, v50, vcc
	v_lshl_add_u64 v[122:123], v[68:69], 0, v[80:81]
	v_pk_fma_f32 v[64:65], v[94:95], v[94:95], v[64:65]
	v_lshlrev_b32_e32 v81, 2, v50
	v_mov_b32_e32 v50, v62
	v_mov_b32_e32 v51, v58
	v_mov_b32_e32 v58, v63
	v_pk_add_f32 v[50:51], v[50:51], v[58:59]
	v_mov_b32_e32 v52, v64
	v_mov_b32_e32 v53, v60
	v_pk_add_f32 v[50:51], v[50:51], v[52:53]
	v_mov_b32_e32 v60, v65
	v_pk_add_f32 v[50:51], v[50:51], v[60:61]
	ds_bpermute_b32 v53, v81, v51
	ds_bpermute_b32 v52, v81, v50
	v_xor_b32_e32 v72, 16, v211
	v_cmp_lt_i32_e32 vcc, v72, v79
	v_mov_b32_e32 v83, v1
	v_lshl_add_u64 v[68:69], v[68:69], 0, v[82:83]
	v_cndmask_b32_e32 v58, v211, v72, vcc
	v_lshlrev_b32_e32 v83, 2, v58
	s_waitcnt lgkmcnt(0)
	v_pk_add_f32 v[58:59], v[50:51], v[52:53]
	ds_bpermute_b32 v61, v83, v59
	ds_bpermute_b32 v60, v83, v58
	v_xor_b32_e32 v62, 8, v211
	v_cmp_lt_i32_e32 vcc, v62, v79
	global_load_dwordx4 v[114:117], v[70:71], off
	global_load_dwordx4 v[118:121], v[74:75], off offset:1024
	v_cndmask_b32_e32 v50, v211, v62, vcc
	global_load_dwordx4 v[122:125], v[122:123], off
	s_nop 0
	global_load_dwordx4 v[126:129], v[74:75], off offset:2048
	global_load_dwordx4 v[130:133], v[68:69], off
	global_load_dwordx4 v[134:137], v[74:75], off offset:3072
	v_lshlrev_b32_e32 v105, 2, v50
	s_waitcnt lgkmcnt(0)
	v_pk_add_f32 v[68:69], v[58:59], v[60:61]
	ds_bpermute_b32 v71, v105, v69
	ds_bpermute_b32 v70, v105, v68
	v_xor_b32_e32 v62, 4, v211
	v_cmp_lt_i32_e32 vcc, v62, v79
	v_xor_b32_e32 v72, 2, v211
	global_load_dwordx4 v[54:57], v[92:93], off
	global_load_dwordx4 v[50:53], v[92:93], off offset:1024
	v_cndmask_b32_e32 v58, v211, v62, vcc
	v_lshlrev_b32_e32 v143, 2, v58
	s_waitcnt lgkmcnt(0)
	v_pk_add_f32 v[68:69], v[68:69], v[70:71]
	ds_bpermute_b32 v71, v143, v69
	ds_bpermute_b32 v70, v143, v68
	global_load_dwordx4 v[62:65], v[66:67], off
	global_load_dwordx4 v[58:61], v[66:67], off offset:1024
	v_cmp_lt_i32_e32 vcc, v72, v79
	v_xor_b32_e32 v103, 1, v211
	v_mov_b32_e32 v100, v27
	v_cndmask_b32_e32 v72, v211, v72, vcc
	v_lshlrev_b32_e32 v145, 2, v72
	s_waitcnt lgkmcnt(0)
	v_pk_add_f32 v[138:139], v[68:69], v[70:71]
	global_load_dwordx4 v[70:73], v[66:67], off offset:2048
	s_nop 0
	global_load_dwordx4 v[66:69], v[66:67], off offset:3072
	ds_bpermute_b32 v141, v145, v139
	ds_bpermute_b32 v140, v145, v138
	v_cmp_lt_i32_e32 vcc, v103, v79
	v_mov_b32_e32 v101, v23
	v_mov_b32_e32 v98, v26
	v_cndmask_b32_e32 v79, v211, v103, vcc
	v_lshlrev_b32_e32 v79, 2, v79
	s_waitcnt lgkmcnt(0)
	v_pk_add_f32 v[138:139], v[138:139], v[140:141]
	ds_bpermute_b32 v141, v79, v139
	ds_bpermute_b32 v140, v79, v138
	v_mov_b32_e32 v99, v22
	v_pk_mul_f32 v[100:101], v[100:101], v[100:101]
	v_mov_b32_e32 v102, v43
	v_mov_b32_e32 v103, v39
	v_mov_b32_e32 v94, v28
	v_mov_b32_e32 v95, v24
	v_pk_fma_f32 v[98:99], v[98:99], v[98:99], v[100:101]
	v_mov_b32_e32 v100, v42
	v_mov_b32_e32 v101, v38
	v_pk_mul_f32 v[102:103], v[102:103], v[102:103]
	v_pk_fma_f32 v[94:95], v[94:95], v[94:95], v[98:99]
	v_mov_b32_e32 v98, v44
	v_mov_b32_e32 v99, v40
	v_pk_fma_f32 v[100:101], v[100:101], v[100:101], v[102:103]
	s_mov_b32 s0, 0x358637bd
	v_pk_fma_f32 v[98:99], v[98:99], v[98:99], v[100:101]
	s_waitcnt lgkmcnt(0)
	v_pk_add_f32 v[100:101], v[138:139], v[140:141]
	v_mov_b64_e32 v[138:139], s[0:1]
	s_mov_b32 s8, 0x3a800000
	v_pk_fma_f32 v[100:101], v[100:101], s[8:9], v[138:139] op_sel_hi:[1,0,0]
	s_mov_b32 s6, 0x800000
	v_mul_f32_e32 v102, 0x4b800000, v101
	v_cmp_gt_f32_e32 vcc, s6, v101
	v_cmp_gt_f32_e64 s[0:1], s6, v100
	v_mov_b32_e32 v96, v29
	v_cndmask_b32_e32 v101, v101, v102, vcc
	v_mul_f32_e32 v102, 0x4b800000, v100
	v_rsq_f32_e32 v101, v101
	v_cndmask_b32_e64 v100, v100, v102, s[0:1]
	v_rsq_f32_e32 v100, v100
	v_mov_b32_e32 v97, v25
	v_pk_fma_f32 v[94:95], v[96:97], v[96:97], v[94:95]
	v_mov_b32_e32 v96, v45
	v_mov_b32_e32 v97, v41
	v_pk_fma_f32 v[140:141], v[96:97], v[96:97], v[98:99]
	v_mul_f32_e32 v96, 0x45800000, v101
	v_cndmask_b32_e32 v142, v101, v96, vcc
	v_mul_f32_e32 v96, 0x45800000, v100
	v_cndmask_b32_e64 v144, v100, v96, s[0:1]
	v_pk_add_f32 v[100:101], v[106:107], 1.0 op_sel_hi:[1,0]
	global_load_dwordx4 v[96:99], v[92:93], off offset:2048
	v_pk_mul_f32 v[106:107], v[110:111], v[100:101]
	v_pk_add_f32 v[100:101], v[108:109], 1.0 op_sel_hi:[1,0]
	s_waitcnt vmcnt(0)
; template <int R>
; DI void norm_rows(const Params& p, int layer, int which, int t0, int tstep, int lane) {
;     ...
; #pragma unroll
;   for (int r = 0; r < R; ++r) {
;     ss[r] = 0.f;
; #pragma unroll
;     for (int j = 0; j < 4; ++j) ss[r] += v[r][j].x * v[r][j].x + v[r][j].y * v[r][j].y + v[r][j].z * v[r][j].z + v[r][j].w * v[r][j].w;
;   }
; #pragma unroll
;   for (int o = 32; o >= 1; o >>= 1)
; #pragma unroll
;     for (int r = 0; r < R; ++r) ss[r] += __shfl_xor(ss[r], o);
; #pragma unroll
;   for (int r = 0; r < R; ++r) ss[r] = rsqrtf(ss[r] * (1.f / 1024.f) + EPSV);
;   float4 mm[4], sh[4];
; #pragma unroll
;   for (int j = 0; j < 4; ++j) {
;     int col = lane * 4 + 256 * j;
;     float4 gg = *(const float4*)(g + col);
;     float4 sc = *(const float4*)(md + 1024 + col);
;     sh[j] = *(const float4*)(md + col);
;     mm[j] = make_float4(gg.x * (1.f + sc.x), gg.y * (1.f + sc.y), gg.z * (1.f + sc.z), gg.w * (1.f + sc.w));
;   }
; #pragma unroll
;   for (int j = 0; j < 4; ++j) {
;     int col = lane * 4 + 256 * j;
; #pragma unroll
;     for (int r = 0; r < R; ++r)
;       *(uint2*)(p.H + (size_t)(t0 + r * tstep) * LDK + col) =
;           make_uint2(pack_bf16(v[r][j].x * ss[r] * mm[j].x + sh[j].x, v[r][j].y * ss[r] * mm[j].y + sh[j].y),
;                      pack_bf16(v[r][j].z * ss[r] * mm[j].z + sh[j].z, v[r][j].w * ss[r] * mm[j].w + sh[j].w));
	v_pk_add_f32 v[110:111], v[116:117], 1.0 op_sel_hi:[1,0]
	v_pk_mul_f32 v[108:109], v[112:113], v[100:101]
	global_load_dwordx4 v[100:103], v[92:93], off offset:3072
	v_pk_add_f32 v[92:93], v[114:115], 1.0 op_sel_hi:[1,0]
	v_pk_mul_f32 v[18:19], v[18:19], v[142:143] op_sel_hi:[1,0]
	v_pk_mul_f32 v[20:21], v[20:21], v[142:143] op_sel_hi:[1,0]
	v_pk_mul_f32 v[92:93], v[118:119], v[92:93]
	v_pk_mul_f32 v[110:111], v[120:121], v[110:111]
	v_pk_mul_f32 v[14:15], v[14:15], v[142:143] op_sel_hi:[1,0]
	v_pk_mul_f32 v[16:17], v[16:17], v[142:143] op_sel_hi:[1,0]
	v_pk_add_f32 v[112:113], v[122:123], 1.0 op_sel_hi:[1,0]
	v_pk_mul_f32 v[32:33], v[32:33], v[144:145] op_sel_hi:[1,0]
	v_pk_fma_f32 v[18:19], v[18:19], v[106:107], v[54:55]
	v_pk_fma_f32 v[20:21], v[20:21], v[108:109], v[56:57]
	v_cvt_pk_bf16_f32 v18, v18, v19
	v_cvt_pk_bf16_f32 v19, v20, v21
	v_pk_mul_f32 v[20:21], v[46:47], v[144:145] op_sel_hi:[1,0]
	v_pk_mul_f32 v[46:47], v[48:49], v[144:145] op_sel_hi:[1,0]
	v_mov_b32_e32 v120, v63
	v_mov_b32_e32 v121, v59
	v_pk_fma_f32 v[14:15], v[14:15], v[92:93], v[50:51]
	v_pk_fma_f32 v[16:17], v[16:17], v[110:111], v[52:53]
	v_mov_b32_e32 v48, v62
	v_mov_b32_e32 v49, v58
	v_pk_mul_f32 v[120:121], v[120:121], v[120:121]
	v_pk_fma_f32 v[20:21], v[106:107], v[20:21], v[54:55]
	v_pk_fma_f32 v[46:47], v[46:47], v[108:109], v[56:57]
	v_cvt_pk_bf16_f32 v14, v14, v15
	v_cvt_pk_bf16_f32 v15, v16, v17
	v_pk_mul_f32 v[16:17], v[30:31], v[144:145] op_sel_hi:[1,0]
	v_mov_b32_e32 v30, v64
	v_mov_b32_e32 v31, v60
	v_pk_fma_f32 v[48:49], v[48:49], v[48:49], v[120:121]
	v_mov_b32_e32 v122, v71
	v_mov_b32_e32 v123, v67
	v_cvt_pk_bf16_f32 v20, v20, v21
	v_cvt_pk_bf16_f32 v21, v46, v47
	v_mov_b32_e32 v46, v65
	v_mov_b32_e32 v47, v61
	v_pk_fma_f32 v[30:31], v[30:31], v[30:31], v[48:49]
	v_mov_b32_e32 v120, v70
	v_mov_b32_e32 v121, v66
	v_pk_mul_f32 v[122:123], v[122:123], v[122:123]
	v_pk_fma_f32 v[30:31], v[46:47], v[46:47], v[30:31]
	v_mov_b32_e32 v46, v72
	v_mov_b32_e32 v47, v68
	v_pk_fma_f32 v[120:121], v[120:121], v[120:121], v[122:123]
	v_mov_b32_e32 v48, v73
	v_mov_b32_e32 v49, v69
	v_pk_fma_f32 v[46:47], v[46:47], v[46:47], v[120:121]
	v_pk_fma_f32 v[16:17], v[16:17], v[92:93], v[50:51]
	v_pk_fma_f32 v[46:47], v[48:49], v[48:49], v[46:47]
	v_mov_b32_e32 v48, v30
	v_mov_b32_e32 v49, v94
	v_mov_b32_e32 v94, v31
	v_pk_add_f32 v[30:31], v[48:49], v[94:95]
	v_mov_b32_e32 v48, v46
	v_mov_b32_e32 v49, v140
	v_pk_add_f32 v[30:31], v[30:31], v[48:49]
	v_mov_b32_e32 v140, v47
	v_pk_add_f32 v[30:31], v[30:31], v[140:141]
	ds_bpermute_b32 v47, v81, v31
	ds_bpermute_b32 v46, v81, v30
	v_pk_fma_f32 v[32:33], v[32:33], v[110:111], v[52:53]
	v_cvt_pk_bf16_f32 v16, v16, v17
	v_cvt_pk_bf16_f32 v17, v32, v33
	v_pk_add_f32 v[116:117], v[130:131], 1.0 op_sel_hi:[1,0]
	s_waitcnt lgkmcnt(0)
	v_pk_add_f32 v[30:31], v[30:31], v[46:47]
	ds_bpermute_b32 v33, v83, v31
	ds_bpermute_b32 v32, v83, v30
	v_pk_add_f32 v[118:119], v[132:133], 1.0 op_sel_hi:[1,0]
	v_pk_mul_f32 v[116:117], v[134:135], v[116:117]
	v_pk_mul_f32 v[118:119], v[136:137], v[118:119]
	v_pk_mul_f32 v[2:3], v[2:3], v[142:143] op_sel_hi:[1,0]
	s_waitcnt lgkmcnt(0)
	v_pk_add_f32 v[30:31], v[30:31], v[32:33]
	ds_bpermute_b32 v33, v105, v31
	ds_bpermute_b32 v32, v105, v30
	v_pk_mul_f32 v[4:5], v[4:5], v[142:143] op_sel_hi:[1,0]
	v_pk_mul_f32 v[12:13], v[12:13], v[144:145] op_sel_hi:[1,0]
	v_pk_add_f32 v[114:115], v[124:125], 1.0 op_sel_hi:[1,0]
	v_pk_mul_f32 v[112:113], v[126:127], v[112:113]
	s_waitcnt lgkmcnt(0)
	v_pk_add_f32 v[30:31], v[30:31], v[32:33]
	ds_bpermute_b32 v33, v143, v31
	ds_bpermute_b32 v32, v143, v30
	s_waitcnt vmcnt(0)
	v_pk_fma_f32 v[2:3], v[2:3], v[116:117], v[100:101]
	v_pk_fma_f32 v[4:5], v[4:5], v[118:119], v[102:103]
	v_cvt_pk_bf16_f32 v2, v2, v3
	v_cvt_pk_bf16_f32 v3, v4, v5
	s_waitcnt lgkmcnt(0)
	v_pk_add_f32 v[30:31], v[30:31], v[32:33]
	ds_bpermute_b32 v33, v145, v31
	ds_bpermute_b32 v32, v145, v30
	v_pk_mul_f32 v[4:5], v[10:11], v[144:145] op_sel_hi:[1,0]
	v_pk_fma_f32 v[12:13], v[12:13], v[118:119], v[102:103]
	v_pk_fma_f32 v[4:5], v[4:5], v[116:117], v[100:101]
	v_pk_mul_f32 v[114:115], v[128:129], v[114:115]
	s_waitcnt lgkmcnt(0)
	v_pk_add_f32 v[30:31], v[30:31], v[32:33]
	ds_bpermute_b32 v33, v79, v31
	ds_bpermute_b32 v32, v79, v30
	v_cvt_pk_bf16_f32 v4, v4, v5
	v_pk_mul_f32 v[6:7], v[6:7], v[142:143] op_sel_hi:[1,0]
	v_pk_mul_f32 v[8:9], v[8:9], v[142:143] op_sel_hi:[1,0]
	v_pk_fma_f32 v[6:7], v[6:7], v[112:113], v[96:97]
	s_waitcnt lgkmcnt(0)
; template <int R>
; DI void norm_rows(const Params& p, int layer, int which, int t0, int tstep, int lane) {
;     ...
;   for (int r = 0; r < R; ++r) ss[r] = rsqrtf(ss[r] * (1.f / 1024.f) + EPSV);
;   float4 mm[4], sh[4];
; #pragma unroll
;   for (int j = 0; j < 4; ++j) {
;     int col = lane * 4 + 256 * j;
;     float4 gg = *(const float4*)(g + col);
;     float4 sc = *(const float4*)(md + 1024 + col);
;     sh[j] = *(const float4*)(md + col);
;     mm[j] = make_float4(gg.x * (1.f + sc.x), gg.y * (1.f + sc.y), gg.z * (1.f + sc.z), gg.w * (1.f + sc.w));
;   }
; #pragma unroll
;   for (int j = 0; j < 4; ++j) {
;     int col = lane * 4 + 256 * j;
; #pragma unroll
;     for (int r = 0; r < R; ++r)
;       *(uint2*)(p.H + (size_t)(t0 + r * tstep) * LDK + col) =
;           make_uint2(pack_bf16(v[r][j].x * ss[r] * mm[j].x + sh[j].x, v[r][j].y * ss[r] * mm[j].y + sh[j].y),
;                      pack_bf16(v[r][j].z * ss[r] * mm[j].z + sh[j].z, v[r][j].w * ss[r] * mm[j].w + sh[j].w));
;   }
	v_pk_add_f32 v[10:11], v[30:31], v[32:33]
	v_pk_fma_f32 v[8:9], v[8:9], v[114:115], v[98:99]
	v_pk_fma_f32 v[10:11], v[10:11], s[8:9], v[138:139] op_sel_hi:[1,0,0]
	v_cvt_pk_bf16_f32 v6, v6, v7
	v_mul_f32_e32 v5, 0x4b800000, v11
	v_cmp_gt_f32_e32 vcc, s6, v11
	v_cvt_pk_bf16_f32 v7, v8, v9
	v_pk_mul_f32 v[8:9], v[34:35], v[144:145] op_sel_hi:[1,0]
	v_cndmask_b32_e32 v5, v11, v5, vcc
	v_rsq_f32_e32 v11, v5
	v_cvt_pk_bf16_f32 v5, v12, v13
	v_pk_mul_f32 v[34:35], v[36:37], v[144:145] op_sel_hi:[1,0]
	v_pk_fma_f32 v[8:9], v[8:9], v[112:113], v[96:97]
	v_mul_f32_e32 v12, 0x45800000, v11
	v_cndmask_b32_e32 v12, v11, v12, vcc
	v_pk_mul_f32 v[26:27], v[26:27], v[12:13] op_sel_hi:[1,0]
	v_pk_mul_f32 v[28:29], v[28:29], v[12:13] op_sel_hi:[1,0]
	v_pk_mul_f32 v[22:23], v[22:23], v[12:13] op_sel_hi:[1,0]
	v_pk_mul_f32 v[24:25], v[24:25], v[12:13] op_sel_hi:[1,0]
	v_pk_fma_f32 v[26:27], v[106:107], v[26:27], v[54:55]
	v_pk_fma_f32 v[28:29], v[28:29], v[108:109], v[56:57]
	v_pk_fma_f32 v[22:23], v[22:23], v[92:93], v[50:51]
	v_pk_fma_f32 v[24:25], v[24:25], v[110:111], v[52:53]
	v_cvt_pk_bf16_f32 v26, v26, v27
	v_cvt_pk_bf16_f32 v27, v28, v29
	v_cvt_pk_bf16_f32 v22, v22, v23
	v_cvt_pk_bf16_f32 v23, v24, v25
	v_pk_mul_f32 v[24:25], v[42:43], v[12:13] op_sel_hi:[1,0]
	v_pk_mul_f32 v[28:29], v[44:45], v[12:13] op_sel_hi:[1,0]
	v_mul_f32_e32 v11, 0x4b800000, v10
	v_cmp_gt_f32_e32 vcc, s6, v10
	v_pk_fma_f32 v[24:25], v[24:25], v[112:113], v[96:97]
	v_pk_fma_f32 v[28:29], v[28:29], v[114:115], v[98:99]
	v_cndmask_b32_e32 v10, v10, v11, vcc
	v_cvt_pk_bf16_f32 v24, v24, v25
	v_cvt_pk_bf16_f32 v25, v28, v29
	v_pk_mul_f32 v[28:29], v[38:39], v[12:13] op_sel_hi:[1,0]
	v_rsq_f32_e32 v13, v10
	v_pk_fma_f32 v[28:29], v[28:29], v[116:117], v[100:101]
	global_store_dwordx2 v[90:91], v[18:19], off
	global_store_dwordx2 v[88:89], v[20:21], off
	global_store_dwordx2 v[86:87], v[26:27], off
	v_cvt_pk_bf16_f32 v28, v28, v29
	v_pk_mul_f32 v[10:11], v[40:41], v[12:13] op_sel_hi:[1,0]
	v_pk_fma_f32 v[34:35], v[34:35], v[114:115], v[98:99]
	v_pk_fma_f32 v[10:11], v[10:11], v[118:119], v[102:103]
	v_cvt_pk_bf16_f32 v8, v8, v9
	v_cvt_pk_bf16_f32 v29, v10, v11
	v_mul_f32_e32 v10, 0x45800000, v13
	v_cndmask_b32_e32 v10, v13, v10, vcc
	v_pk_mul_f32 v[12:13], v[62:63], v[10:11] op_sel_hi:[1,0]
	v_pk_mul_f32 v[18:19], v[64:65], v[10:11] op_sel_hi:[1,0]
	v_pk_fma_f32 v[12:13], v[106:107], v[12:13], v[54:55]
	v_pk_fma_f32 v[18:19], v[108:109], v[18:19], v[56:57]
	v_cvt_pk_bf16_f32 v12, v12, v13
	v_cvt_pk_bf16_f32 v13, v18, v19
	global_store_dwordx2 v[84:85], v[12:13], off
	global_store_dwordx2 v[90:91], v[14:15], off offset:512
	global_store_dwordx2 v[88:89], v[16:17], off offset:512
	global_store_dwordx2 v[86:87], v[22:23], off offset:512
	v_pk_mul_f32 v[12:13], v[58:59], v[10:11] op_sel_hi:[1,0]
	v_pk_mul_f32 v[14:15], v[60:61], v[10:11] op_sel_hi:[1,0]
	v_pk_fma_f32 v[12:13], v[12:13], v[92:93], v[50:51]
	v_pk_fma_f32 v[14:15], v[14:15], v[110:111], v[52:53]
	v_cvt_pk_bf16_f32 v9, v34, v35
	v_cvt_pk_bf16_f32 v12, v12, v13
	v_cvt_pk_bf16_f32 v13, v14, v15
	global_store_dwordx2 v[84:85], v[12:13], off offset:512
	global_store_dwordx2 v[90:91], v[6:7], off offset:1024
	global_store_dwordx2 v[88:89], v[8:9], off offset:1024
	global_store_dwordx2 v[86:87], v[24:25], off offset:1024
	v_pk_mul_f32 v[6:7], v[70:71], v[10:11] op_sel_hi:[1,0]
	v_pk_mul_f32 v[8:9], v[72:73], v[10:11] op_sel_hi:[1,0]
	v_pk_fma_f32 v[6:7], v[6:7], v[112:113], v[96:97]
	v_pk_fma_f32 v[8:9], v[8:9], v[114:115], v[98:99]
	v_cvt_pk_bf16_f32 v6, v6, v7
	v_cvt_pk_bf16_f32 v7, v8, v9
	global_store_dwordx2 v[84:85], v[6:7], off offset:1024
	global_store_dwordx2 v[90:91], v[2:3], off offset:1536
	global_store_dwordx2 v[88:89], v[4:5], off offset:1536
	global_store_dwordx2 v[86:87], v[28:29], off offset:1536
	v_pk_mul_f32 v[2:3], v[66:67], v[10:11] op_sel_hi:[1,0]
	v_pk_mul_f32 v[4:5], v[68:69], v[10:11] op_sel_hi:[1,0]
	v_pk_fma_f32 v[2:3], v[2:3], v[116:117], v[100:101]
	v_pk_fma_f32 v[4:5], v[4:5], v[118:119], v[102:103]
	v_cvt_pk_bf16_f32 v2, v2, v3
	v_cvt_pk_bf16_f32 v3, v4, v5
	s_mov_b64 s[0:1], 0
	global_store_dwordx2 v[84:85], v[2:3], off offset:1536
	s_branch .LBB0_877
